# P5 EpiScale epilogue: lane-cooperative ssq prefetch; attention: VALU row-sum instead of ones-MFMA, K frags hoisted, 32-bit saddr DMA addressing, persistent -m accumulator-init block (no per-tile v_mov
# speedup vs baseline: 1.0383x; 1.0383x over previous
; #define LAS __attribute__((address_space(3)))
; __device__ __forceinline__ float bf_lo(unsigned u) { return __uint_as_float(u << 16); }
; __device__ __forceinline__ float bf_hi(unsigned u) { return __uint_as_float(u & 0xffff0000u); }
; #define MFMA32(a, b, c) __builtin_amdgcn_mfma_f32_32x32x16_bf16((a), (b), (c), 0, 0, 0)
; __device__ __forceinline__ void scan_step(const LAS unsigned char* ring, float gl, f32x16 (&S)[4], const u32x2 (&uu)[8], LAS bf16_t* ob, int wave, int lane, int r, int h) {
;     ...
;     for (int kb = 0; kb < 4; ++kb) { sb[kb][0] = pack8(S[kb], 0); sb[kb][1] = pack8(S[kb], 8); }
;     f32x16 VN[2];
; #pragma unroll
;     for (int ib = 0; ib < 2; ++ib)
; #pragma unroll
;         for (int g4 = 0; g4 < 4; ++g4) { const u32x2 u2 = uu[ib * 4 + g4];
;             VN[ib][4 * g4] = bf_lo(u2.x); VN[ib][4 * g4 + 1] = bf_hi(u2.x); VN[ib][4 * g4 + 2] = bf_lo(u2.y); VN[ib][4 * g4 + 3] = bf_hi(u2.y); }
; #pragma unroll
;     for (int kb = 0; kb < 4; ++kb)
; #pragma unroll
;         for (int s = 0; s < 2; ++s)
; #pragma unroll
;             for (int ib = 0; ib < 2; ++ib) VN[ib] = MFMA32(ldsfrag(lNW, ib * 8 + kb * 2 + s, lane), sb[kb][s], VN[ib]);
;     f32x16 Oa[2];
; #pragma unroll
;     for (int ib = 0; ib < 2; ++ib)
; #pragma unroll
;         for (int ii = 0; ii < 16; ++ii) Oa[ib][ii] = 0.f;
; #pragma unroll
;     for (int kb = 0; kb < 4; ++kb)
; #pragma unroll
;         for (int s = 0; s < 2; ++s)
; #pragma unroll
;             for (int ib = 0; ib < 2; ++ib) Oa[ib] = MFMA32(ldsfrag(lQG, ib * 8 + kb * 2 + s, lane), sb[kb][s], Oa[ib]);
; __device__ __forceinline__ void scan_unit(const Params& P, LAS unsigned char* lds, int su) {
;     ...
;             if (n + 1 < nsteps) {
;                 const unsigned char* chn = ch0 + (size_t)(n + 1) * 4 * CH_BYTES;
; #pragma unroll
;                 for (int i = 0; i < 8; ++i) un[i] = *(const u32x2*)(chn + 49152 + (wave * 8 + i) * 512 + (unsigned)(lane * 8));
;             }
;             scan_step(lds + (n & 1) * SC_RING, GL[unit0 + n * 4], S, uu, (LAS bf16_t*)(lds + SC_OB + (n & 1) * SC_OBSZ), wave, lane, r, h);
.LBB0_671:
.LBB0_672:
	s_and_b32 s5, s3, 1
	s_mul_i32 s3, s5, 0xe000
	v_add_u32_e32 v151, s3, v162
	s_waitcnt vmcnt(6)
	v_lshlrev_b32_e32 v136, 16, v88
	v_and_b32_e32 v137, 0xffff0000, v88
	v_lshlrev_b32_e32 v138, 16, v89
	v_and_b32_e32 v139, 0xffff0000, v89
	s_waitcnt vmcnt(5)
	v_lshlrev_b32_e32 v140, 16, v86
	v_and_b32_e32 v141, 0xffff0000, v86
	v_lshlrev_b32_e32 v142, 16, v87
	v_and_b32_e32 v143, 0xffff0000, v87
	ds_read_b128 v[86:89], v151
	s_waitcnt vmcnt(3)
	v_lshlrev_b32_e32 v128, 16, v94
	v_and_b32_e32 v129, 0xffff0000, v94
	v_lshlrev_b32_e32 v130, 16, v95
	v_and_b32_e32 v131, 0xffff0000, v95
	v_lshlrev_b32_e32 v132, 16, v90
	v_and_b32_e32 v133, 0xffff0000, v90
	v_lshlrev_b32_e32 v134, 16, v91
	v_and_b32_e32 v135, 0xffff0000, v91
	v_lshlrev_b32_e32 v112, 16, v92
	v_and_b32_e32 v113, 0xffff0000, v92
	v_lshlrev_b32_e32 v114, 16, v93
	v_and_b32_e32 v115, 0xffff0000, v93
	ds_read_b128 v[90:93], v151 offset:8192
	ds_read_b128 v[94:97], v151 offset:1024
	v_cvt_pk_bf16_f32 v2, v16, v17
	v_cvt_pk_bf16_f32 v3, v18, v19
	v_cvt_pk_bf16_f32 v4, v20, v21
	v_cvt_pk_bf16_f32 v5, v22, v23
	s_waitcnt vmcnt(2)
	v_lshlrev_b32_e32 v116, 16, v84
	v_and_b32_e32 v117, 0xffff0000, v84
	v_lshlrev_b32_e32 v118, 16, v85
	v_and_b32_e32 v119, 0xffff0000, v85
	s_waitcnt vmcnt(1)
	v_lshlrev_b32_e32 v120, 16, v82
	v_and_b32_e32 v121, 0xffff0000, v82
	v_lshlrev_b32_e32 v122, 16, v83
	v_and_b32_e32 v123, 0xffff0000, v83
	s_waitcnt vmcnt(0)
	v_lshlrev_b32_e32 v124, 16, v80
	v_and_b32_e32 v125, 0xffff0000, v80
	v_lshlrev_b32_e32 v126, 16, v81
	v_and_b32_e32 v127, 0xffff0000, v81
	s_cmp_lt_u32 s4, s95
	s_cbranch_scc0 .Lscan_nopf
	global_load_dwordx2 v[158:159], v[6:7], off offset:-2048
	global_load_dwordx2 v[156:157], v[6:7], off offset:-1536
	global_load_dwordx2 v[154:155], v[6:7], off offset:-1024
	global_load_dwordx2 v[152:153], v[6:7], off offset:-512
	global_load_dwordx2 v[14:15], v[6:7], off
	global_load_dwordx2 v[12:13], v[6:7], off offset:512
	global_load_dwordx2 v[10:11], v[6:7], off offset:1024
	global_load_dwordx2 v[8:9], v[6:7], off offset:1536
.Lscan_nopf:
	ds_read_b128 v[80:83], v151 offset:9216
	s_waitcnt lgkmcnt(3)
	v_mfma_f32_32x32x16_bf16 v[128:143], v[86:89], v[2:5], v[128:143]
	v_cvt_pk_bf16_f32 v166, v24, v25
	v_cvt_pk_bf16_f32 v167, v26, v27
	v_cvt_pk_bf16_f32 v168, v28, v29
	v_cvt_pk_bf16_f32 v169, v30, v31
	v_cvt_pk_bf16_f32 v172, v32, v33
	v_cvt_pk_bf16_f32 v173, v34, v35
	v_cvt_pk_bf16_f32 v174, v36, v37
	s_waitcnt lgkmcnt(2)
	v_mfma_f32_32x32x16_bf16 v[112:127], v[90:93], v[2:5], v[112:127]
	v_cvt_pk_bf16_f32 v175, v38, v39
	ds_read_b128 v[84:87], v151 offset:3072
	v_cvt_pk_bf16_f32 v178, v40, v41
	v_cvt_pk_bf16_f32 v179, v42, v43
	v_cvt_pk_bf16_f32 v180, v44, v45
	v_cvt_pk_bf16_f32 v181, v46, v47
	v_cvt_pk_bf16_f32 v182, v48, v49
	s_waitcnt lgkmcnt(1)
	v_mfma_f32_32x32x16_bf16 v[112:127], v[80:83], v[166:169], v[112:127]
	ds_read_b128 v[80:83], v151 offset:2048
	v_cvt_pk_bf16_f32 v183, v50, v51
	v_cvt_pk_bf16_f32 v184, v52, v53
	v_cvt_pk_bf16_f32 v185, v54, v55
	v_cvt_pk_bf16_f32 v186, v56, v57
	v_cvt_pk_bf16_f32 v187, v58, v59
	v_cvt_pk_bf16_f32 v188, v60, v61
	v_mfma_f32_32x32x16_bf16 v[128:143], v[94:97], v[166:169], v[128:143]
	v_cvt_pk_bf16_f32 v189, v62, v63
	v_cvt_pk_bf16_f32 v190, v64, v65
	v_cvt_pk_bf16_f32 v191, v66, v67
	v_cvt_pk_bf16_f32 v192, v68, v69
	v_cvt_pk_bf16_f32 v193, v70, v71
	v_cvt_pk_bf16_f32 v194, v72, v73
	v_cvt_pk_bf16_f32 v195, v74, v75
	s_waitcnt lgkmcnt(0)
	v_mfma_f32_32x32x16_bf16 v[128:143], v[80:83], v[172:175], v[128:143]
	ds_read_b128 v[80:83], v151 offset:10240
	ds_read_b128 v[88:91], v151 offset:11264
	v_cvt_pk_bf16_f32 v196, v76, v77
	v_cvt_pk_bf16_f32 v197, v78, v79
	s_ashr_i32 s3, s2, 31
	s_lshl_b64 s[10:11], s[2:3], 2
	s_add_u32 s10, s33, s10
	s_addc_u32 s11, s60, s11
	s_waitcnt lgkmcnt(1)
	v_mfma_f32_32x32x16_bf16 v[112:127], v[80:83], v[172:175], v[112:127]
	ds_read_b128 v[80:83], v151 offset:4096
	v_mfma_f32_32x32x16_bf16 v[128:143], v[84:87], v[178:181], v[128:143]
	ds_read_b128 v[84:87], v151 offset:5120
	s_waitcnt lgkmcnt(2)
	v_mfma_f32_32x32x16_bf16 v[112:127], v[88:91], v[178:181], v[112:127]
	s_waitcnt lgkmcnt(1)
	v_mfma_f32_32x32x16_bf16 v[128:143], v[80:83], v[182:185], v[128:143]
	ds_read_b128 v[80:83], v151 offset:12288
	ds_read_b128 v[88:91], v151 offset:13312
	s_waitcnt lgkmcnt(1)
	v_mfma_f32_32x32x16_bf16 v[112:127], v[80:83], v[182:185], v[112:127]
	ds_read_b128 v[80:83], v151 offset:6144
	v_mfma_f32_32x32x16_bf16 v[128:143], v[84:87], v[186:189], v[128:143]
	ds_read_b128 v[84:87], v151 offset:7168
	s_waitcnt lgkmcnt(2)
	v_mfma_f32_32x32x16_bf16 v[112:127], v[88:91], v[186:189], v[112:127]
	s_waitcnt lgkmcnt(1)
	v_mfma_f32_32x32x16_bf16 v[128:143], v[80:83], v[190:193], v[128:143]
	ds_read_b128 v[80:83], v151 offset:14336
	ds_read_b128 v[88:91], v151 offset:15360
	s_waitcnt lgkmcnt(1)
	v_mfma_f32_32x32x16_bf16 v[112:127], v[80:83], v[190:193], v[112:127]
	ds_read_b128 v[80:83], v151 offset:16384
	ds_read_b128 v[198:201], v151 offset:17408
	s_waitcnt lgkmcnt(1)
	v_mfma_f32_32x32x16_bf16 v[96:111], v[80:83], v[2:5], 0
	ds_read_b128 v[80:83], v151 offset:24576
	ds_read_b128 v[202:205], v151 offset:25600
	v_mfma_f32_32x32x16_bf16 v[128:143], v[84:87], v[194:197], v[128:143]
	v_mfma_f32_32x32x16_bf16 v[112:127], v[88:91], v[194:197], v[112:127]
	s_waitcnt lgkmcnt(1)
	v_mfma_f32_32x32x16_bf16 v[80:95], v[80:83], v[2:5], 0
	v_mfma_f32_32x32x16_bf16 v[96:111], v[198:201], v[166:169], v[96:111]
	s_waitcnt lgkmcnt(0)
	v_mfma_f32_32x32x16_bf16 v[80:95], v[202:205], v[166:169], v[80:95]
	ds_read_b128 v[2:5], v151 offset:18432
	ds_read_b128 v[166:169], v151 offset:19456
	s_waitcnt lgkmcnt(1)
; #define MFMA32(a, b, c) __builtin_amdgcn_mfma_f32_32x32x16_bf16((a), (b), (c), 0, 0, 0)
; #define SCHED_FENCE() __builtin_amdgcn_sched_barrier(0)
; __device__ __forceinline__ void scan_step(const LAS unsigned char* ring, float gl, f32x16 (&S)[4], const u32x2 (&uu)[8], LAS bf16_t* ob, int wave, int lane, int r, int h) {
;     ...
;             for (int ib = 0; ib < 2; ++ib) Oa[ib] = MFMA32(ldsfrag(lQG, ib * 8 + kb * 2 + s, lane), sb[kb][s], Oa[ib]);
;     SCHED_FENCE();
;     bf16x8 vnb[2][2];
; #pragma unroll
;     for (int jb = 0; jb < 2; ++jb) { vnb[jb][0] = pack8(VN[jb], 0); vnb[jb][1] = pack8(VN[jb], 8); }
; #pragma unroll
;     for (int jb = 0; jb < 2; ++jb)
; #pragma unroll
;         for (int s = 0; s < 2; ++s)
; #pragma unroll
;             for (int ib = 0; ib < 2; ++ib) Oa[ib] = MFMA32(ldsfrag(lAQK, ib * 4 + jb * 2 + s, lane), vnb[jb][s], Oa[ib]);
; #pragma unroll
;     for (int kb = 0; kb < 4; ++kb) S[kb] = S[kb] * gl;
	v_mfma_f32_32x32x16_bf16 v[96:111], v[2:5], v[172:175], v[96:111]
	ds_read_b128 v[2:5], v151 offset:26624
	ds_read_b128 v[198:201], v151 offset:27648
	s_waitcnt lgkmcnt(1)
	v_mfma_f32_32x32x16_bf16 v[80:95], v[2:5], v[172:175], v[80:95]
	v_mfma_f32_32x32x16_bf16 v[96:111], v[166:169], v[178:181], v[96:111]
	ds_read_b128 v[2:5], v151 offset:20480
	ds_read_b128 v[166:169], v151 offset:21504
	s_waitcnt lgkmcnt(2)
	v_mfma_f32_32x32x16_bf16 v[80:95], v[198:201], v[178:181], v[80:95]
	s_waitcnt lgkmcnt(1)
	v_mfma_f32_32x32x16_bf16 v[96:111], v[2:5], v[182:185], v[96:111]
	ds_read_b128 v[2:5], v151 offset:28672
	ds_read_b128 v[172:175], v151 offset:29696
	s_waitcnt lgkmcnt(1)
	v_mfma_f32_32x32x16_bf16 v[80:95], v[2:5], v[182:185], v[80:95]
	v_mfma_f32_32x32x16_bf16 v[96:111], v[166:169], v[186:189], v[96:111]
	ds_read_b128 v[2:5], v151 offset:22528
	ds_read_b128 v[166:169], v151 offset:23552
	s_waitcnt lgkmcnt(2)
	v_mfma_f32_32x32x16_bf16 v[80:95], v[172:175], v[186:189], v[80:95]
	s_waitcnt lgkmcnt(1)
	v_mfma_f32_32x32x16_bf16 v[96:111], v[2:5], v[190:193], v[96:111]
	ds_read_b128 v[2:5], v151 offset:30720
	ds_read_b128 v[172:175], v151 offset:31744
	global_load_dword v178, v1, s[10:11]
	s_waitcnt lgkmcnt(1)
	v_mfma_f32_32x32x16_bf16 v[80:95], v[2:5], v[190:193], v[80:95]
	v_mfma_f32_32x32x16_bf16 v[96:111], v[166:169], v[194:197], v[96:111]
	s_waitcnt lgkmcnt(0)
	v_mfma_f32_32x32x16_bf16 v[80:95], v[172:175], v[194:197], v[80:95]
	ds_read_b128 v[2:5], v151 offset:49152
	v_cvt_pk_bf16_f32 v128, v128, v129
	v_cvt_pk_bf16_f32 v129, v130, v131
	v_cvt_pk_bf16_f32 v130, v132, v133
	v_cvt_pk_bf16_f32 v131, v134, v135
	ds_read_b128 v[132:135], v151 offset:50176
	v_cvt_pk_bf16_f32 v112, v112, v113
	v_cvt_pk_bf16_f32 v113, v114, v115
	v_cvt_pk_bf16_f32 v114, v116, v117
	s_waitcnt lgkmcnt(1)
	v_mfma_f32_32x32x16_bf16 v[96:111], v[2:5], v[128:131], v[96:111]
	ds_read_b128 v[2:5], v151 offset:53248
	ds_read_b128 v[166:169], v151 offset:54272
	v_cvt_pk_bf16_f32 v115, v118, v119
	v_cvt_pk_bf16_f32 v120, v120, v121
	v_cvt_pk_bf16_f32 v121, v122, v123
	v_cvt_pk_bf16_f32 v122, v124, v125
	v_cvt_pk_bf16_f32 v123, v126, v127
	s_waitcnt vmcnt(0)
	v_pk_mul_f32 v[30:31], v[30:31], v[178:179] op_sel_hi:[1,0]
	s_waitcnt lgkmcnt(1)
	v_mfma_f32_32x32x16_bf16 v[80:95], v[2:5], v[128:131], v[80:95]
	v_cvt_pk_bf16_f32 v2, v136, v137
	v_cvt_pk_bf16_f32 v3, v138, v139
	v_cvt_pk_bf16_f32 v4, v140, v141
	v_cvt_pk_bf16_f32 v5, v142, v143
	ds_read_b128 v[116:119], v151 offset:52224
	v_pk_mul_f32 v[28:29], v[28:29], v[178:179] op_sel_hi:[1,0]
	v_pk_mul_f32 v[26:27], v[26:27], v[178:179] op_sel_hi:[1,0]
	v_mfma_f32_32x32x16_bf16 v[96:111], v[132:135], v[2:5], v[96:111]
	ds_read_b128 v[132:135], v151 offset:51200
	v_mul_f32_e64 v24, v24, v178
	v_mul_f32_e64 v25, v25, v178
	v_mul_f32_e64 v22, v22, v178
	v_mul_f32_e64 v23, v23, v178
	v_pk_mul_f32 v[20:21], v[20:21], v[178:179] op_sel_hi:[1,0]
	v_pk_mul_f32 v[18:19], v[18:19], v[178:179] op_sel_hi:[1,0]
	v_pk_mul_f32 v[16:17], v[16:17], v[178:179] op_sel_hi:[1,0]
	v_pk_mul_f32 v[46:47], v[46:47], v[178:179] op_sel_hi:[1,0]
	s_waitcnt lgkmcnt(0)
	v_mfma_f32_32x32x16_bf16 v[96:111], v[132:135], v[112:115], v[96:111]
	ds_read_b128 v[132:135], v151 offset:55296
	ds_read_b128 v[136:139], v151 offset:56320
	v_mul_f32_e64 v44, v44, v178
	v_mul_f32_e64 v45, v45, v178
	v_mul_f32_e64 v42, v42, v178
	v_mul_f32_e64 v43, v43, v178
	v_pk_mul_f32 v[40:41], v[40:41], v[178:179] op_sel_hi:[1,0]
	v_pk_mul_f32 v[38:39], v[38:39], v[178:179] op_sel_hi:[1,0]
	v_pk_mul_f32 v[36:37], v[36:37], v[178:179] op_sel_hi:[1,0]
	v_pk_mul_f32 v[34:35], v[34:35], v[178:179] op_sel_hi:[1,0]
	v_mfma_f32_32x32x16_bf16 v[80:95], v[166:169], v[2:5], v[80:95]
	v_mul_f32_e64 v32, v32, v178
	v_mul_f32_e64 v33, v33, v178
	v_mul_f32_e64 v62, v62, v178
	v_mul_f32_e64 v63, v63, v178
	v_mul_f32_e64 v60, v60, v178
	v_mul_f32_e64 v61, v61, v178
	v_pk_mul_f32 v[58:59], v[58:59], v[178:179] op_sel_hi:[1,0]
	v_pk_mul_f32 v[56:57], v[56:57], v[178:179] op_sel_hi:[1,0]
	v_pk_mul_f32 v[54:55], v[54:55], v[178:179] op_sel_hi:[1,0]
	v_pk_mul_f32 v[52:53], v[52:53], v[178:179] op_sel_hi:[1,0]
	v_mfma_f32_32x32x16_bf16 v[96:111], v[116:119], v[120:123], v[96:111]
	ds_read_b128 v[116:119], v151 offset:32768
	v_mul_f32_e64 v50, v50, v178
	v_mul_f32_e64 v51, v51, v178
	v_mul_f32_e64 v48, v48, v178
	v_mul_f32_e64 v49, v49, v178
	v_pk_mul_f32 v[78:79], v[78:79], v[178:179] op_sel_hi:[1,0]
	v_pk_mul_f32 v[76:77], v[76:77], v[178:179] op_sel_hi:[1,0]
	v_pk_mul_f32 v[74:75], v[74:75], v[178:179] op_sel_hi:[1,0]
	v_pk_mul_f32 v[72:73], v[72:73], v[178:179] op_sel_hi:[1,0]
	s_waitcnt lgkmcnt(2)
; __device__ __forceinline__ bf16_t f2bf(float f) { return (bf16_t)(pk2(f, 0.f) & 0xffffu); }
; __device__ __forceinline__ int crow(int reg, int h) { return (reg & 3) + 8 * (reg >> 2) + 4 * h; }
; #define MFMA32(a, b, c) __builtin_amdgcn_mfma_f32_32x32x16_bf16((a), (b), (c), 0, 0, 0)
; #define SCHED_FENCE() __builtin_amdgcn_sched_barrier(0)
; __device__ __forceinline__ void scan_step(const LAS unsigned char* ring, float gl, f32x16 (&S)[4], const u32x2 (&uu)[8], LAS bf16_t* ob, int wave, int lane, int r, int h) {
;     ...
; #pragma unroll
;     for (int jb = 0; jb < 2; ++jb)
; #pragma unroll
;         for (int s = 0; s < 2; ++s)
; #pragma unroll
;             for (int kb = 0; kb < 4; ++kb) S[kb] = MFMA32(ldsfrag(lKDT, kb * 4 + jb * 2 + s, lane), vnb[jb][s], S[kb]);
;     SCHED_FENCE();
; #pragma unroll
;     for (int ib = 0; ib < 2; ++ib)
; #pragma unroll
;         for (int ii = 0; ii < 16; ++ii) ob[(32 * ib + crow(ii, h)) * 128 + 32 * wave + r] = f2bf(Oa[ib][ii]);
; __device__ __forceinline__ void scan_unit(const Params& P, LAS unsigned char* lds, int su) {
;     ...
;             for (int i = 0; i < 8; ++i) uu[i] = un[i];
;             __syncthreads();
	v_mfma_f32_32x32x16_bf16 v[80:95], v[132:135], v[112:115], v[80:95]
	ds_read_b128 v[124:127], v151 offset:36864
	ds_read_b128 v[132:135], v151 offset:33792
	v_mul_f32_e64 v70, v70, v178
	v_mul_f32_e64 v71, v71, v178
	v_mul_f32_e64 v68, v68, v178
	v_mul_f32_e64 v69, v69, v178
	v_pk_mul_f32 v[66:67], v[66:67], v[178:179] op_sel_hi:[1,0]
	v_pk_mul_f32 v[64:65], v[64:65], v[178:179] op_sel_hi:[1,0]
	s_waitcnt lgkmcnt(3)
	v_mfma_f32_32x32x16_bf16 v[80:95], v[136:139], v[120:123], v[80:95]
	s_waitcnt lgkmcnt(2)
	v_mfma_f32_32x32x16_bf16 v[16:31], v[116:119], v[128:131], v[16:31]
	ds_read_b128 v[116:119], v151 offset:40960
	ds_read_b128 v[136:139], v151 offset:37888
	s_waitcnt lgkmcnt(3)
	v_mfma_f32_32x32x16_bf16 v[32:47], v[124:127], v[128:131], v[32:47]
	ds_read_b128 v[124:127], v151 offset:45056
	ds_read_b128 v[140:143], v151 offset:41984
	s_waitcnt lgkmcnt(3)
	v_mfma_f32_32x32x16_bf16 v[48:63], v[116:119], v[128:131], v[48:63]
	ds_read_b128 v[116:119], v151 offset:46080
	s_waitcnt lgkmcnt(2)
	v_mfma_f32_32x32x16_bf16 v[64:79], v[124:127], v[128:131], v[64:79]
	v_mfma_f32_32x32x16_bf16 v[16:31], v[132:135], v[2:5], v[16:31]
	v_mfma_f32_32x32x16_bf16 v[32:47], v[136:139], v[2:5], v[32:47]
	s_waitcnt lgkmcnt(1)
	v_mfma_f32_32x32x16_bf16 v[48:63], v[140:143], v[2:5], v[48:63]
	s_waitcnt lgkmcnt(0)
	v_mfma_f32_32x32x16_bf16 v[64:79], v[116:119], v[2:5], v[64:79]
	ds_read_b128 v[2:5], v151 offset:34816
	ds_read_b128 v[116:119], v151 offset:35840
	s_waitcnt lgkmcnt(1)
	v_mfma_f32_32x32x16_bf16 v[16:31], v[2:5], v[112:115], v[16:31]
	ds_read_b128 v[2:5], v151 offset:38912
	ds_read_b128 v[124:127], v151 offset:39936
	s_waitcnt lgkmcnt(1)
	v_mfma_f32_32x32x16_bf16 v[32:47], v[2:5], v[112:115], v[32:47]
	ds_read_b128 v[2:5], v151 offset:43008
	ds_read_b128 v[128:131], v151 offset:44032
	s_waitcnt lgkmcnt(1)
	v_mfma_f32_32x32x16_bf16 v[48:63], v[2:5], v[112:115], v[48:63]
	ds_read_b128 v[2:5], v151 offset:47104
	ds_read_b128 v[132:135], v151 offset:48128
	s_waitcnt lgkmcnt(1)
	v_mfma_f32_32x32x16_bf16 v[64:79], v[2:5], v[112:115], v[64:79]
	v_mfma_f32_32x32x16_bf16 v[16:31], v[116:119], v[120:123], v[16:31]
	v_mfma_f32_32x32x16_bf16 v[32:47], v[124:127], v[120:123], v[32:47]
	v_mfma_f32_32x32x16_bf16 v[48:63], v[128:131], v[120:123], v[48:63]
	s_waitcnt lgkmcnt(0)
	v_mfma_f32_32x32x16_bf16 v[64:79], v[132:135], v[120:123], v[64:79]
	v_lshl_add_u32 v2, s5, 14, v0
	v_cvt_pk_bf16_f32 v3, v96, s0
	ds_write_b16 v2, v3
	v_cvt_pk_bf16_f32 v3, v97, s0
	ds_write_b16 v2, v3 offset:256
	v_cvt_pk_bf16_f32 v3, v98, s0
	ds_write_b16 v2, v3 offset:512
	v_cvt_pk_bf16_f32 v3, v99, s0
	ds_write_b16 v2, v3 offset:768
	v_cvt_pk_bf16_f32 v3, v100, s0
	ds_write_b16 v2, v3 offset:2048
	v_cvt_pk_bf16_f32 v3, v101, s0
	ds_write_b16 v2, v3 offset:2304
	v_cvt_pk_bf16_f32 v3, v102, s0
	ds_write_b16 v2, v3 offset:2560
	v_cvt_pk_bf16_f32 v3, v103, s0
	ds_write_b16 v2, v3 offset:2816
	v_cvt_pk_bf16_f32 v3, v104, s0
	ds_write_b16 v2, v3 offset:4096
	v_cvt_pk_bf16_f32 v3, v105, s0
	ds_write_b16 v2, v3 offset:4352
	v_cvt_pk_bf16_f32 v3, v106, s0
	ds_write_b16 v2, v3 offset:4608
	v_cvt_pk_bf16_f32 v3, v107, s0
	ds_write_b16 v2, v3 offset:4864
	v_cvt_pk_bf16_f32 v3, v108, s0
	ds_write_b16 v2, v3 offset:6144
	v_cvt_pk_bf16_f32 v3, v109, s0
	ds_write_b16 v2, v3 offset:6400
	v_cvt_pk_bf16_f32 v3, v110, s0
	ds_write_b16 v2, v3 offset:6656
	v_cvt_pk_bf16_f32 v3, v111, s0
	ds_write_b16 v2, v3 offset:6912
	v_cvt_pk_bf16_f32 v3, v80, s0
	ds_write_b16 v2, v3 offset:8192
	v_cvt_pk_bf16_f32 v3, v81, s0
	ds_write_b16 v2, v3 offset:8448
	v_cvt_pk_bf16_f32 v3, v82, s0
	ds_write_b16 v2, v3 offset:8704
	v_cvt_pk_bf16_f32 v3, v83, s0
	ds_write_b16 v2, v3 offset:8960
	v_cvt_pk_bf16_f32 v3, v84, s0
	ds_write_b16 v2, v3 offset:10240
	v_cvt_pk_bf16_f32 v3, v85, s0
	ds_write_b16 v2, v3 offset:10496
	v_cvt_pk_bf16_f32 v3, v86, s0
	ds_write_b16 v2, v3 offset:10752
	v_cvt_pk_bf16_f32 v3, v87, s0
	ds_write_b16 v2, v3 offset:11008
	v_cvt_pk_bf16_f32 v3, v88, s0
	ds_write_b16 v2, v3 offset:12288
	v_cvt_pk_bf16_f32 v3, v89, s0
	ds_write_b16 v2, v3 offset:12544
	v_cvt_pk_bf16_f32 v3, v90, s0
	ds_write_b16 v2, v3 offset:12800
	v_cvt_pk_bf16_f32 v3, v91, s0
	ds_write_b16 v2, v3 offset:13056
	v_cvt_pk_bf16_f32 v3, v92, s0
	ds_write_b16 v2, v3 offset:14336
	v_cvt_pk_bf16_f32 v3, v93, s0
	ds_write_b16 v2, v3 offset:14592
	v_cvt_pk_bf16_f32 v3, v94, s0
	s_add_i32 s2, s2, 4
	ds_write_b16 v2, v3 offset:14848
	v_cvt_pk_bf16_f32 v3, v95, s0
	s_cmp_eq_u32 s95, s4
	v_lshl_add_u64 v[6:7], v[6:7], 0, s[12:13]
	ds_write_b16 v2, v3 offset:15104
	s_waitcnt lgkmcnt(0)
	s_barrier
	s_cbranch_scc1 .LBB0_674
	v_mov_b64_e32 v[86:87], v[152:153]
	v_mov_b64_e32 v[88:89], v[154:155]
	v_mov_b64_e32 v[90:91], v[156:157]
	v_mov_b64_e32 v[94:95], v[158:159]
	v_mov_b64_e32 v[92:93], v[14:15]
	v_mov_b64_e32 v[84:85], v[12:13]
	v_mov_b64_e32 v[82:83], v[10:11]
	v_mov_b64_e32 v[80:81], v[8:9]
	s_mov_b32 s3, s4
	s_add_i32 s4, s3, 1
	s_cmp_ge_u32 s4, s95
	s_cbranch_scc0 .LBB0_671
	s_branch .LBB0_672

; #define A_WAITBAR(N) asm volatile("s_waitcnt vmcnt(" #N ") lgkmcnt(0)\n\ts_barrier" ::: "memory")
; template <bool DIFF> ...
;     ...
;     bf16x8 bq[KS];
; #pragma unroll
;     for (int f = 0; f < KS; ++f) bq[f] = *(const bf16x8*)(qrow + mp * 64 + f * 16 + h * 8);
;     float m_ = -INFINITY; f32x16 O[4], lacc;
;     const bf16x8 ones = {0x3F80, 0x3F80, 0x3F80, 0x3F80, 0x3F80, 0x3F80, 0x3F80, 0x3F80};
; #pragma unroll
;     for (int ii = 0; ii < 16; ++ii) lacc[ii] = 0.f;
; #pragma unroll
;     for (int db = 0; db < 4; ++db)
; #pragma unroll
;         for (int ii = 0; ii < 16; ++ii) O[db][ii] = 0.f;
;     int goff[5];
; #pragma unroll
;     for (int i = 0; i < 5; ++i) { int op = wave + 8 * i; op = op > 36 ? 36 : op; const bool isk = op < 17; const int slot = (isk ? op : op - 17) * 64 + lane; const int per = isk ? 17 : 20;
;         const int row = slot / per; int pcs = slot - row * per; pcs = pcs > 15 ? 15 : pcs; goff[i] = (row << 10) | (pcs << 4); }
;     ...
;     __syncthreads();
;     asm volatile("s_waitcnt vmcnt(0)" ::: "memory");
;     A_DMA(0, 0, 0);
;     A_WAITBAR(0);
.LBB0_1479:
	v_readfirstlane_b32 s42, v2
	v_readfirstlane_b32 s43, v3
	v_readfirstlane_b32 s40, v4
	v_readfirstlane_b32 s41, v5
	v_readfirstlane_b32 s89, v176
	s_lshr_b32 s86, s89, 6
	s_bfe_u32 s87, s89, 0x10006
	s_lshl_b32 s94, s87, 7
	s_min_u32 s0, s86, 36
	s_cmpk_lt_u32 s89, 0x440
	s_cselect_b64 s[6:7], -1, 0
	s_lshl_b32 s1, s0, 6
	s_add_i32 s8, s1, 0xfffffbc0
	s_and_b64 s[4:5], s[6:7], exec
	v_lshl_add_u64 v[6:7], v[6:7], 0, s[94:95]
	v_lshlrev_b32_e32 v0, 1, v144
	s_cselect_b32 s1, s1, s8
	s_cselect_b32 s4, 17, 20
	v_lshl_add_u64 v[6:7], v[6:7], 0, v[0:1]
	v_or_b32_e32 v0, s1, v206
	v_cvt_f32_ubyte0_e32 v10, s4
	v_cvt_f32_i32_e32 v8, v0
	v_rcp_iflag_f32_e32 v11, v10
	global_load_dwordx4 v[128:131], v[6:7], off
	global_load_dwordx4 v[132:135], v[6:7], off offset:32
	global_load_dwordx4 v[136:139], v[6:7], off offset:64
	global_load_dwordx4 v[140:143], v[6:7], off offset:96
	s_ashr_i32 s1, s1, 30
	v_mul_f32_e32 v6, v8, v11
	v_trunc_f32_e32 v6, v6
	s_or_b32 s1, s1, 1
	v_fma_f32 v7, -v6, v10, v8
	v_cvt_i32_f32_e32 v6, v6
	v_mov_b32_e32 v8, s1
	s_min_u32 s1, s86, 28
	v_cmp_ge_f32_e64 vcc, |v7|, v10
	s_add_i32 s12, s1, 8
	s_cmpk_lt_u32 s89, 0x240
	v_cndmask_b32_e32 v7, 0, v8, vcc
	v_add_u32_e32 v6, v6, v7
	s_cselect_b64 s[8:9], -1, 0
	s_lshl_b32 s1, s12, 6
	v_bfe_i32 v6, v6, 0, 14
	s_add_i32 s10, s1, 0xfffffbc0
	v_mul_i32_i24_e32 v7, s4, v6
	s_and_b64 s[4:5], s[8:9], exec
	s_cselect_b32 s1, s1, s10
	s_cselect_b32 s4, 17, 20
	v_or_b32_e32 v8, s1, v206
	v_cvt_f32_ubyte0_e32 v11, s4
	v_cvt_f32_i32_e32 v10, v8
	v_rcp_iflag_f32_e32 v12, v11
	s_ashr_i32 s1, s1, 30
	s_or_b32 s1, s1, 1
	v_mov_b32_e32 v13, s1
	v_mul_f32_e32 v12, v10, v12
	v_trunc_f32_e32 v12, v12
	v_fma_f32 v10, -v12, v11, v10
	v_cvt_i32_f32_e32 v12, v12
	v_cmp_ge_f32_e64 vcc, |v10|, v11
	s_min_u32 s1, s86, 20
	s_add_i32 s13, s1, 16
	v_cndmask_b32_e32 v10, 0, v13, vcc
	v_add_u32_e32 v10, v12, v10
	s_cmp_lt_u32 s89, 64
	v_bfe_i32 v10, v10, 0, 14
	s_cselect_b64 s[10:11], -1, 0
	s_lshl_b32 s1, s13, 6
	v_mul_i32_i24_e32 v11, s4, v10
	s_addk_i32 s1, 0xfbc0
	v_sub_u32_e32 v8, v8, v11
	s_and_b64 s[4:5], s[10:11], exec
	v_min_i32_e32 v8, 15, v8
	s_cselect_b32 s1, 0x400, s1
	s_cselect_b32 s4, 17, 20
	v_lshlrev_b32_e32 v12, 4, v8
	v_or_b32_e32 v8, s1, v206
	v_cvt_f32_ubyte0_e32 v13, s4
	v_cvt_f32_i32_e32 v11, v8
	v_rcp_iflag_f32_e32 v14, v13
	v_lshl_or_b32 v15, v10, 10, v12
	s_ashr_i32 s1, s1, 30
	s_or_b32 s1, s1, 1
	v_mul_f32_e32 v10, v11, v14
	v_trunc_f32_e32 v10, v10
	v_fma_f32 v11, -v10, v13, v11
	v_cvt_i32_f32_e32 v10, v10
	v_mov_b32_e32 v14, s1
	v_cmp_ge_f32_e64 vcc, |v11|, v13
	s_min_u32 s1, s86, 12
	s_movk_i32 s14, 0xffec
	v_cndmask_b32_e32 v11, 0, v14, vcc
	v_add_u32_e32 v10, v10, v11
	v_bfe_i32 v10, v10, 0, 14
	v_mul_i32_i24_e32 v11, s4, v10
	v_sub_u32_e32 v8, v8, v11
	v_min_i32_e32 v8, 15, v8
	s_add_i32 s4, s1, 24
	v_lshlrev_b32_e32 v14, 4, v8
	v_lshl_add_u32 v8, s4, 6, v145
	v_lshl_or_b32 v16, v10, 10, v14
	v_mul_u32_u24_e32 v10, 0xcccd, v8
	v_lshrrev_b32_e32 v11, 20, v10
	v_mad_i32_i24 v8, v11, s14, v8
	s_min_u32 s1, s86, 4
	v_min_i32_e32 v8, 15, v8
	s_or_b32 s5, s1, 32
	v_lshrrev_b32_e32 v10, 10, v10
	v_lshlrev_b32_e32 v17, 4, v8
	v_lshl_add_u32 v8, s5, 6, v145
	v_sub_u32_e32 v0, v0, v7
	v_or_b32_e32 v18, v17, v10
	v_mul_u32_u24_e32 v10, 0xcccd, v8
	v_min_i32_e32 v0, 15, v0
	v_lshrrev_b32_e32 v11, 20, v10
	v_lshlrev_b32_e32 v0, 4, v0
	v_mad_i32_i24 v8, v11, s14, v8
	v_lshl_or_b32 v6, v6, 10, v0
	v_min_i32_e32 v8, 15, v8
	v_lshrrev_b32_e32 v10, 10, v10
	v_lshlrev_b32_e32 v19, 4, v8
	s_add_i32 s83, s81, -1
	v_ashrrev_i32_e32 v21, 10, v6
	v_or_b32_e32 v20, v19, v10
	v_min_i32_e32 v10, s83, v21
	s_lshl_b32 s14, s0, 10
	v_ashrrev_i32_e32 v11, 31, v10
	s_add_i32 s15, s14, 0x8800
	v_cndmask_b32_e64 v9, v3, v5, s[6:7]
	v_cndmask_b32_e64 v8, v2, v4, s[6:7]
	v_lshlrev_b64 v[10:11], 10, v[10:11]
	s_and_b64 s[0:1], s[6:7], exec
	v_lshl_add_u64 v[10:11], v[8:9], 0, v[10:11]
	v_and_b32_e32 v0, 0x3f0, v0
	s_cselect_b32 s0, s14, s15
	s_barrier
	s_waitcnt vmcnt(0)
	v_lshl_add_u64 v[10:11], v[10:11], 0, v[0:1]
	s_add_i32 m0, s0, 0
	v_ashrrev_i32_e32 v22, 10, v15
	global_load_lds_dwordx4 v[10:11], off
	v_min_i32_e32 v10, s83, v22
	s_lshl_b32 s12, s12, 10
	v_ashrrev_i32_e32 v11, 31, v10
	s_add_i32 s15, s12, 0x8800
	v_cndmask_b32_e64 v7, v3, v5, s[8:9]
	v_cndmask_b32_e64 v6, v2, v4, s[8:9]
	v_lshlrev_b64 v[10:11], 10, v[10:11]
	s_and_b64 s[0:1], s[8:9], exec
	v_lshl_add_u64 v[10:11], v[6:7], 0, v[10:11]
	v_and_b32_e32 v12, 0x3f0, v12
	v_mov_b32_e32 v13, v1
	s_cselect_b32 s0, s12, s15
	v_lshl_add_u64 v[10:11], v[10:11], 0, v[12:13]
	s_add_i32 m0, s0, 0
	v_ashrrev_i32_e32 v23, 10, v16
	global_load_lds_dwordx4 v[10:11], off
	v_min_i32_e32 v10, s83, v23
	s_lshl_b32 s13, s13, 10
	v_ashrrev_i32_e32 v11, 31, v10
	s_add_i32 s15, s13, 0x8800
	v_cndmask_b32_e64 v5, v3, v5, s[10:11]
	v_cndmask_b32_e64 v4, v2, v4, s[10:11]
	v_lshlrev_b64 v[10:11], 10, v[10:11]
	s_and_b64 s[0:1], s[10:11], exec
	v_lshl_add_u64 v[10:11], v[4:5], 0, v[10:11]
	v_and_b32_e32 v14, 0x3f0, v14
	v_mov_b32_e32 v15, v1
	s_cselect_b32 s0, 0x4000, s15
	v_lshl_add_u64 v[10:11], v[10:11], 0, v[14:15]
	s_add_i32 m0, s0, 0
	v_ashrrev_i32_e32 v24, 10, v18
	global_load_lds_dwordx4 v[10:11], off
	v_min_i32_e32 v10, s83, v24
	v_ashrrev_i32_e32 v11, 31, v10
	v_lshlrev_b64 v[10:11], 10, v[10:11]
	s_lshl_b32 s0, s4, 10
	v_lshl_add_u64 v[10:11], v[2:3], 0, v[10:11]
	v_and_b32_e32 v16, 0x3f0, v17
	v_mov_b32_e32 v17, v1
	s_add_i32 s4, s0, 0
	v_lshl_add_u64 v[10:11], v[10:11], 0, v[16:17]
	s_add_i32 m0, s4, 0x8800
	v_ashrrev_i32_e32 v20, 10, v20
	global_load_lds_dwordx4 v[10:11], off
	v_min_i32_e32 v10, s83, v20
	v_ashrrev_i32_e32 v11, 31, v10
	v_lshlrev_b64 v[10:11], 10, v[10:11]
	s_lshl_b32 s0, s5, 10
	v_lshl_add_u64 v[10:11], v[2:3], 0, v[10:11]
	v_and_b32_e32 v18, 0x3f0, v19
	v_mov_b32_e32 v19, v1
	s_add_i32 s5, s0, 0
	v_lshl_add_u64 v[10:11], v[10:11], 0, v[18:19]
	s_add_i32 m0, s5, 0x8800
	v_mov_b32_e32 v178, v14
	global_load_lds_dwordx4 v[10:11], off
	s_waitcnt vmcnt(0) lgkmcnt(0)
	s_barrier
; #define LAS __attribute__((address_space(3)))
; #define A_WAITBAR(N) asm volatile("s_waitcnt vmcnt(" #N ") lgkmcnt(0)\n\ts_barrier" ::: "memory")
; template <bool DIFF> ...
;     ...
;     float m_ = -INFINITY; f32x16 O[4], lacc;
;     const bf16x8 ones = {0x3F80, 0x3F80, 0x3F80, 0x3F80, 0x3F80, 0x3F80, 0x3F80, 0x3F80};
; #pragma unroll
;     for (int ii = 0; ii < 16; ++ii) lacc[ii] = 0.f;
; #pragma unroll
;     for (int db = 0; db < 4; ++db)
; #pragma unroll
;         for (int ii = 0; ii < 16; ++ii) O[db][ii] = 0.f;
;     int goff[5];
; #pragma unroll
;     for (int i = 0; i < 5; ++i) { int op = wave + 8 * i; op = op > 36 ? 36 : op; const bool isk = op < 17; const int slot = (isk ? op : op - 17) * 64 + lane; const int per = isk ? 17 : 20;
;         const int row = slot / per; int pcs = slot - row * per; pcs = pcs > 15 ? 15 : pcs; goff[i] = (row << 10) | (pcs << 4); }
;     ...
;     __syncthreads();
;     asm volatile("s_waitcnt vmcnt(0)" ::: "memory");
;     A_DMA(0, 0, 0);
;     A_WAITBAR(0);
;     const int q4 = (lane & 15) >> 2, p4 = lane & 3, g1 = (lane >> 4) & 1;
;     const LAS unsigned char* vb0 = lds + A_VB + (4 * h + q4) * A_VSTR + 32 * g1 + 8 * p4;
;     ...
;     const bool late = false;
;     bool first = true, pact = false;
;     bf16x8 pk[2][2];
;     int k3 = 0;
;     for (int t = 0; t < NT; ++t) {
;         const int k3n = (k3 == 2) ? 0 : k3 + 1;
;         if (t + 1 < NT) A_DMA(t + 1, k3n, (t + 1) & 3);
;     ...
;             for (int ks = 0; ks < KS; ++ks) {
;                 const bf16x8 a0 = *(const LAS bf16x8*)(kbuf + r * 272 + (ks * 16 + h * 8) * 2);
;                 const bf16x8 a1 = *(const LAS bf16x8*)(kbuf + (32 + r) * 272 + (ks * 16 + h * 8) * 2);
	v_mov_b32_e32 v14, v1
	v_mov_b32_e32 v172, v0
	v_mov_b32_e32 v174, v12
	v_mov_b32_e32 v180, v16
	v_mov_b32_e32 v182, v18
	v_add_u32_e32 v155, 64, v20
	v_add_u32_e32 v157, 64, v24
	v_add_u32_e32 v159, 64, v23
	v_add_u32_e32 v161, 64, v22
	v_add_u32_e32 v163, 64, v21
	v_mov_b32_e32 v0, v1
	v_mov_b32_e32 v2, v1
	v_mov_b32_e32 v3, v1
	v_mov_b32_e32 v4, v1
	v_mov_b32_e32 v5, v1
	v_mov_b32_e32 v6, v1
	v_mov_b32_e32 v7, v1
	v_mov_b32_e32 v8, v1
	v_mov_b32_e32 v9, v1
	v_mov_b32_e32 v10, v1
	v_mov_b32_e32 v11, v1
	v_mov_b32_e32 v12, v1
	v_mov_b64_e32 v[46:47], v[14:15]
	v_mov_b64_e32 v[30:31], v[14:15]
	v_mov_b64_e32 v[62:63], v[14:15]
	v_mov_b64_e32 v[78:79], v[14:15]
	v_mov_b64_e32 v[94:95], v[14:15]
	s_mov_b32 s0, 0
	s_lshr_b32 s88, s89, 7
	s_sub_i32 s1, s81, 64
	s_add_i32 s90, s14, 0
	s_add_i32 s92, s12, 0
	s_add_i32 s93, s13, 0
	v_add_u32_e32 v148, s94, v208
	s_mov_b64 s[12:13], -1
	v_mov_b32_e32 v153, 0xff800000
	v_mov_b64_e32 v[44:45], v[12:13]
	v_mov_b64_e32 v[42:43], v[10:11]
	v_mov_b64_e32 v[40:41], v[8:9]
	v_mov_b64_e32 v[38:39], v[6:7]
	v_mov_b64_e32 v[36:37], v[4:5]
	v_mov_b64_e32 v[34:35], v[2:3]
	v_mov_b64_e32 v[32:33], v[0:1]
	v_mov_b64_e32 v[28:29], v[12:13]
	v_mov_b64_e32 v[26:27], v[10:11]
	v_mov_b64_e32 v[24:25], v[8:9]
	v_mov_b64_e32 v[22:23], v[6:7]
	v_mov_b64_e32 v[20:21], v[4:5]
	v_mov_b64_e32 v[18:19], v[2:3]
	v_mov_b64_e32 v[16:17], v[0:1]
	v_mov_b64_e32 v[60:61], v[12:13]
	v_mov_b64_e32 v[58:59], v[10:11]
	v_mov_b64_e32 v[56:57], v[8:9]
	v_mov_b64_e32 v[54:55], v[6:7]
	v_mov_b64_e32 v[52:53], v[4:5]
	v_mov_b64_e32 v[50:51], v[2:3]
	v_mov_b64_e32 v[48:49], v[0:1]
	v_mov_b64_e32 v[76:77], v[12:13]
	v_mov_b64_e32 v[74:75], v[10:11]
	v_mov_b64_e32 v[72:73], v[8:9]
	v_mov_b64_e32 v[70:71], v[6:7]
	v_mov_b64_e32 v[68:69], v[4:5]
	v_mov_b64_e32 v[66:67], v[2:3]
	v_mov_b64_e32 v[64:65], v[0:1]
	v_mov_b64_e32 v[92:93], v[12:13]
	v_mov_b64_e32 v[90:91], v[10:11]
	v_mov_b64_e32 v[88:89], v[8:9]
	v_mov_b64_e32 v[86:87], v[6:7]
	v_mov_b64_e32 v[84:85], v[4:5]
	v_mov_b64_e32 v[82:83], v[2:3]
	v_mov_b64_e32 v[80:81], v[0:1]
	s_mov_b32 s14, 0
	s_mov_b32 s15, 0
	s_waitcnt vmcnt(0)
	s_and_b64 s[16:17], s[6:7], exec
	s_cselect_b64 s[44:45], s[40:41], s[42:43]
	s_and_b64 s[16:17], s[8:9], exec
	s_cselect_b64 s[46:47], s[40:41], s[42:43]
	s_and_b64 s[16:17], s[10:11], exec
	s_cselect_b64 s[48:49], s[40:41], s[42:43]
	v_mov_b32_e32 v240, 0
	v_mov_b32_e32 v241, 0
	v_mov_b32_e32 v242, 0
	v_mov_b32_e32 v243, 0
.LBB0_1480:
	s_add_i32 s16, s14, 1
	s_cmp_lg_u32 s14, 2
	s_cselect_b32 s84, s16, 0
	s_mul_i32 s16, s14, 0x4400
	v_add_u32_e32 v0, s16, v148
	ds_read_b128 v[2:5], v0
	ds_read_b128 v[10:13], v0 offset:8704
	ds_read_b128 v[6:9], v0 offset:32
	ds_read_b128 v[212:215], v0 offset:8736
	ds_read_b128 v[216:219], v0 offset:64
	ds_read_b128 v[224:227], v0 offset:8768
	ds_read_b128 v[220:223], v0 offset:96
	ds_read_b128 v[228:231], v0 offset:8800
	s_add_i32 s85, s15, 1
	s_cmp_ge_u32 s85, s80
	s_cbranch_scc1 .LBB0_1482
	s_and_b32 s16, s85, 3
	s_mulk_i32 s16, 0x5000
	s_add_i32 s18, s16, 0x8800
	s_mul_i32 s19, s84, 0x4400
	v_add_u32_e32 v0, s0, v163
	v_add_u32_e32 v14, s0, v161
	v_min_i32_e32 v0, s83, v0
	v_min_i32_e32 v14, s83, v14
	v_lshl_add_u32 v0, v0, 10, v172
	v_lshl_add_u32 v14, v14, 10, v174
	s_and_b64 s[16:17], s[6:7], exec
	s_cselect_b32 s16, s19, s18
	s_add_i32 m0, s90, s16
	s_nop 0
	global_load_lds_dwordx4 v0, s[44:45]
	s_and_b64 s[16:17], s[8:9], exec
	s_cselect_b32 s16, s19, s18
	s_add_i32 m0, s92, s16
	v_add_u32_e32 v15, s0, v159
	global_load_lds_dwordx4 v14, s[46:47]
	v_min_i32_e32 v15, s83, v15
	v_lshl_add_u32 v15, v15, 10, v178
	s_and_b64 s[16:17], s[10:11], exec
	s_cselect_b32 s16, s19, s18
	s_add_i32 m0, s93, s16
	v_add_u32_e32 v0, s0, v157
	global_load_lds_dwordx4 v15, s[48:49]
	v_min_i32_e32 v0, s83, v0
	v_lshl_add_u32 v0, v0, 10, v180
	s_add_i32 m0, s18, s4
	v_add_u32_e32 v14, s0, v155
	global_load_lds_dwordx4 v0, s[42:43]
	v_min_i32_e32 v14, s83, v14
	v_lshl_add_u32 v14, v14, 10, v182
	s_add_i32 m0, s18, s5
	s_nop 0
	global_load_lds_dwordx4 v14, s[42:43]
; #define LAS __attribute__((address_space(3)))
; __device__ __forceinline__ int crow(int reg, int h) { return (reg & 3) + 8 * (reg >> 2) + 4 * h; }
; #define MFMA32(a, b, c) __builtin_amdgcn_mfma_f32_32x32x16_bf16((a), (b), (c), 0, 0, 0)
; template <bool DIFF> ...
;     ...
;         const bool active = split ? ((t % NG) == grp) : (t <= my_lim);
;         if (active) {
;             const LAS unsigned char* kbuf = lds + A_KB + k3 * 17408 + mp * 128;
;             const float cin = first ? 0.f : -m_;
;             f32x16 s0, s1;
; #pragma unroll
;             for (int ii = 0; ii < 16; ++ii) { s0[ii] = cin; s1[ii] = cin; }
; #pragma unroll
;             for (int ks = 0; ks < KS; ++ks) {
;                 const bf16x8 a0 = *(const LAS bf16x8*)(kbuf + r * 272 + (ks * 16 + h * 8) * 2);
;                 const bf16x8 a1 = *(const LAS bf16x8*)(kbuf + (32 + r) * 272 + (ks * 16 + h * 8) * 2);
;                 s0 = MFMA32(a0, bq[ks], s0); s1 = MFMA32(a1, bq[ks], s1);
;             }
;             if (t * 64 + 64 > nkeys) {
; #pragma unroll
;                 for (int ii = 0; ii < 16; ++ii) { const int key = t * 64 + crow(ii, h); if (key >= nkeys) s0[ii] = -INFINITY; if (key + 32 >= nkeys) s1[ii] = -INFINITY; }
;             }
.LBB0_1482:
	s_and_b32 s77, s15, 3
	s_cmp_eq_u32 s77, s88
	s_cselect_b64 s[16:17], -1, 0
	s_cmp_le_i32 s15, s82
	v_cndmask_b32_e64 v0, 0, 1, s[16:17]
	s_cselect_b64 s[16:17], -1, 0
	v_cndmask_b32_e64 v14, 0, 1, s[16:17]
	s_and_b64 s[16:17], exec, s[2:3]
	v_readfirstlane_b32 s15, v0
	v_readfirstlane_b32 s16, v14
	s_cselect_b32 s15, s15, s16
	s_bitcmp1_b32 s15, 0
	s_cselect_b64 s[78:79], -1, 0
	s_bitcmp0_b32 s15, 0
	s_cbranch_scc1 .LBB0_1493
	s_cmp_le_u32 s0, s1
	s_waitcnt lgkmcnt(0)
	v_mfma_f32_32x32x16_bf16 v[112:127], v[2:5], v[128:131], v[80:95]
	v_mfma_f32_32x32x16_bf16 v[96:111], v[10:13], v[128:131], v[80:95]
	v_mfma_f32_32x32x16_bf16 v[112:127], v[6:9], v[132:135], v[112:127]
	v_mfma_f32_32x32x16_bf16 v[96:111], v[212:215], v[132:135], v[96:111]
	v_mfma_f32_32x32x16_bf16 v[112:127], v[216:219], v[136:139], v[112:127]
	v_mfma_f32_32x32x16_bf16 v[96:111], v[224:227], v[136:139], v[96:111]
	v_mfma_f32_32x32x16_bf16 v[112:127], v[220:223], v[140:143], v[112:127]
	v_mfma_f32_32x32x16_bf16 v[96:111], v[228:231], v[140:143], v[96:111]
	s_cbranch_scc1 .LBB0_1485
	v_add_u32_e32 v0, s0, v177
	v_add_u32_e32 v2, 32, v0
	v_cmp_gt_u32_e32 vcc, s81, v2
	v_add_u32_e32 v2, 1, v0
	v_cmp_gt_u32_e64 s[44:45], s81, v2
	v_add_u32_e32 v2, 33, v0
	v_cmp_gt_u32_e64 s[14:15], s81, v2
	v_add_u32_e32 v2, 2, v0
	v_cmp_gt_u32_e64 s[48:49], s81, v2
	v_add_u32_e32 v2, 34, v0
	v_cmp_gt_u32_e64 s[16:17], s81, v2
	v_add_u32_e32 v2, 3, v0
	v_cmp_gt_u32_e64 s[50:51], s81, v2
	v_add_u32_e32 v2, 35, v0
	v_cmp_gt_u32_e64 s[18:19], s81, v2
	v_add_u32_e32 v2, 8, v0
	v_cmp_gt_u32_e64 s[52:53], s81, v2
	v_add_u32_e32 v2, 40, v0
	v_cmp_gt_u32_e64 s[20:21], s81, v2
	v_add_u32_e32 v2, 9, v0
	v_cmp_gt_u32_e64 s[54:55], s81, v2
	v_add_u32_e32 v2, 41, v0
	v_cmp_gt_u32_e64 s[22:23], s81, v2
	v_add_u32_e32 v2, 10, v0
	v_cmp_gt_u32_e64 s[56:57], s81, v2
	v_add_u32_e32 v2, 42, v0
	v_cmp_gt_u32_e64 s[24:25], s81, v2
	v_add_u32_e32 v2, 11, v0
	v_cmp_gt_u32_e64 s[58:59], s81, v2
	v_add_u32_e32 v2, 43, v0
	v_cmp_gt_u32_e64 s[26:27], s81, v2
	v_add_u32_e32 v2, 16, v0
	v_cmp_gt_u32_e64 s[60:61], s81, v2
	v_add_u32_e32 v2, 48, v0
	v_cmp_gt_u32_e64 s[28:29], s81, v2
	v_add_u32_e32 v2, 17, v0
	v_cmp_gt_u32_e64 s[62:63], s81, v2
	v_add_u32_e32 v2, 49, v0
	v_cmp_gt_u32_e64 s[30:31], s81, v2
	v_add_u32_e32 v2, 18, v0
	v_cmp_gt_u32_e64 s[64:65], s81, v2
	v_add_u32_e32 v2, 50, v0
	v_cmp_gt_u32_e64 s[34:35], s81, v2
	v_add_u32_e32 v2, 19, v0
	v_cmp_gt_u32_e64 s[66:67], s81, v2
	v_add_u32_e32 v2, 51, v0
	v_cmp_gt_u32_e64 s[36:37], s81, v2
	v_add_u32_e32 v2, 24, v0
	v_cmp_gt_u32_e64 s[68:69], s81, v2
	v_add_u32_e32 v2, 56, v0
	v_cmp_gt_u32_e64 s[38:39], s81, v2
	v_add_u32_e32 v2, 25, v0
	v_cmp_gt_u32_e64 s[70:71], s81, v2
	v_add_u32_e32 v2, 57, v0
	v_cmp_gt_u32_e64 s[42:43], s81, v2
	v_add_u32_e32 v2, 26, v0
	v_cmp_gt_u32_e64 s[72:73], s81, v2
	v_add_u32_e32 v2, 58, v0
	v_cmp_gt_u32_e64 s[46:47], s81, v2
	v_add_u32_e32 v2, 27, v0
	v_cmp_gt_u32_e64 s[74:75], s81, v2
	s_or_b64 s[72:73], s[74:75], s[72:73]
	s_or_b64 s[70:71], s[72:73], s[70:71]
	s_or_b64 s[68:69], s[70:71], s[68:69]
	s_or_b64 s[66:67], s[68:69], s[66:67]
	s_or_b64 s[64:65], s[66:67], s[64:65]
	s_or_b64 s[62:63], s[64:65], s[62:63]
	s_or_b64 s[60:61], s[62:63], s[60:61]
	s_or_b64 s[58:59], s[60:61], s[58:59]
	s_or_b64 s[56:57], s[58:59], s[56:57]
	s_or_b64 s[54:55], s[56:57], s[54:55]
	s_or_b64 s[52:53], s[54:55], s[52:53]
	s_or_b64 s[50:51], s[52:53], s[50:51]
	s_or_b64 s[48:49], s[50:51], s[48:49]
	v_cmp_gt_u32_e64 s[40:41], s81, v0
	s_or_b64 s[44:45], s[48:49], s[44:45]
	s_or_b64 s[40:41], s[44:45], s[40:41]
	v_add_u32_e32 v0, 59, v0
	v_cndmask_b32_e64 v112, v211, v112, s[40:41]
	v_cmp_gt_u32_e64 s[40:41], s81, v0
	v_cndmask_b32_e64 v127, v211, v127, s[74:75]
	v_cndmask_b32_e64 v126, v211, v126, s[72:73]
	v_cndmask_b32_e64 v111, v211, v111, s[40:41]
	s_or_b64 s[40:41], s[40:41], s[46:47]
	v_cndmask_b32_e64 v110, v211, v110, s[40:41]
	s_or_b64 s[40:41], s[40:41], s[42:43]
	s_or_b64 s[38:39], s[40:41], s[38:39]
	s_or_b64 s[36:37], s[38:39], s[36:37]
	s_or_b64 s[34:35], s[36:37], s[34:35]
	s_or_b64 s[30:31], s[34:35], s[30:31]
	s_or_b64 s[28:29], s[30:31], s[28:29]
	s_or_b64 s[26:27], s[28:29], s[26:27]
	s_or_b64 s[24:25], s[26:27], s[24:25]
	s_or_b64 s[22:23], s[24:25], s[22:23]
	s_or_b64 s[20:21], s[22:23], s[20:21]
	s_or_b64 s[18:19], s[20:21], s[18:19]
	s_or_b64 s[16:17], s[18:19], s[16:17]
	s_or_b64 s[14:15], s[16:17], s[14:15]
	s_or_b64 vcc, s[14:15], vcc
	v_cndmask_b32_e64 v125, v211, v125, s[70:71]
	v_cndmask_b32_e64 v124, v211, v124, s[68:69]
	v_cndmask_b32_e64 v123, v211, v123, s[66:67]
	v_cndmask_b32_e64 v122, v211, v122, s[64:65]
	v_cndmask_b32_e64 v121, v211, v121, s[62:63]
	v_cndmask_b32_e64 v120, v211, v120, s[60:61]
	v_cndmask_b32_e64 v119, v211, v119, s[58:59]
	v_cndmask_b32_e64 v118, v211, v118, s[56:57]
	v_cndmask_b32_e64 v117, v211, v117, s[54:55]
	v_cndmask_b32_e64 v116, v211, v116, s[52:53]
	v_cndmask_b32_e64 v115, v211, v115, s[50:51]
	v_cndmask_b32_e64 v114, v211, v114, s[48:49]
	v_cndmask_b32_e64 v113, v211, v113, s[44:45]
	v_cndmask_b32_e64 v109, v211, v109, s[40:41]
	v_cndmask_b32_e64 v108, v211, v108, s[38:39]
	v_cndmask_b32_e64 v107, v211, v107, s[36:37]
	v_cndmask_b32_e64 v106, v211, v106, s[34:35]
	v_cndmask_b32_e64 v105, v211, v105, s[30:31]
	v_cndmask_b32_e64 v104, v211, v104, s[28:29]
	v_cndmask_b32_e64 v103, v211, v103, s[26:27]
	v_cndmask_b32_e64 v102, v211, v102, s[24:25]
	v_cndmask_b32_e64 v101, v211, v101, s[22:23]
	v_cndmask_b32_e64 v100, v211, v100, s[20:21]
	v_cndmask_b32_e64 v99, v211, v99, s[18:19]
	v_cndmask_b32_e64 v98, v211, v98, s[16:17]
	v_cndmask_b32_e64 v97, v211, v97, s[14:15]
	v_cndmask_b32_e32 v96, v211, v96, vcc

; template <bool DIFF> ...
;     ...
;             if (first || __any(mx > 6.0f)) {
;                 const float dl = first ? mx : ((mx > 6.0f) ? mx : 0.f);
;                 const float alpha = first ? 1.0f : __builtin_amdgcn_exp2f(-dl);
;                 m_ = first ? mx : m_ + dl; first = false;
;                 lacc = lacc * alpha;
; #pragma unroll
;                 for (int ii = 0; ii < 16; ++ii) { s0[ii] -= dl; s1[ii] -= dl; }
; #pragma unroll
;                 for (int db = 0; db < 4; ++db) O[db] = O[db] * alpha;
;             }
.LBB0_1490:
	s_andn2_b64 vcc, exec, s[14:15]
	s_cbranch_vccnz .LBB0_1492
	v_exp_f32_e64 v3, -v0
	v_add_f32_e32 v5, v153, v0
	v_pk_add_f32 v[112:113], v[112:113], v[0:1] op_sel_hi:[1,0] neg_lo:[0,1] neg_hi:[0,1]
	v_pk_add_f32 v[96:97], v[96:97], v[0:1] op_sel_hi:[1,0] neg_lo:[0,1] neg_hi:[0,1]
	v_cndmask_b32_e64 v4, v3, 1.0, s[12:13]
	v_pk_add_f32 v[114:115], v[114:115], v[0:1] op_sel_hi:[1,0] neg_lo:[0,1] neg_hi:[0,1]
	v_pk_add_f32 v[98:99], v[98:99], v[0:1] op_sel_hi:[1,0] neg_lo:[0,1] neg_hi:[0,1]
	v_pk_add_f32 v[116:117], v[116:117], v[0:1] op_sel_hi:[1,0] neg_lo:[0,1] neg_hi:[0,1]
	v_pk_add_f32 v[100:101], v[100:101], v[0:1] op_sel_hi:[1,0] neg_lo:[0,1] neg_hi:[0,1]
	v_pk_add_f32 v[118:119], v[118:119], v[0:1] op_sel_hi:[1,0] neg_lo:[0,1] neg_hi:[0,1]
	v_pk_add_f32 v[102:103], v[102:103], v[0:1] op_sel_hi:[1,0] neg_lo:[0,1] neg_hi:[0,1]
	v_pk_add_f32 v[120:121], v[120:121], v[0:1] op_sel_hi:[1,0] neg_lo:[0,1] neg_hi:[0,1]
	v_pk_add_f32 v[104:105], v[104:105], v[0:1] op_sel_hi:[1,0] neg_lo:[0,1] neg_hi:[0,1]
	v_pk_add_f32 v[122:123], v[122:123], v[0:1] op_sel_hi:[1,0] neg_lo:[0,1] neg_hi:[0,1]
	v_pk_add_f32 v[106:107], v[106:107], v[0:1] op_sel_hi:[1,0] neg_lo:[0,1] neg_hi:[0,1]
	v_pk_add_f32 v[124:125], v[124:125], v[0:1] op_sel_hi:[1,0] neg_lo:[0,1] neg_hi:[0,1]
	v_pk_add_f32 v[108:109], v[108:109], v[0:1] op_sel_hi:[1,0] neg_lo:[0,1] neg_hi:[0,1]
	v_pk_add_f32 v[126:127], v[126:127], v[0:1] op_sel_hi:[1,0] neg_lo:[0,1] neg_hi:[0,1]
	v_pk_add_f32 v[110:111], v[110:111], v[0:1] op_sel_hi:[1,0] neg_lo:[0,1] neg_hi:[0,1]
	v_cndmask_b32_e64 v153, v5, v2, s[12:13]
	v_pk_mul_f32 v[46:47], v[46:47], v[4:5] op_sel_hi:[1,0]
	v_pk_mul_f32 v[44:45], v[44:45], v[4:5] op_sel_hi:[1,0]
	v_pk_mul_f32 v[42:43], v[42:43], v[4:5] op_sel_hi:[1,0]
	v_pk_mul_f32 v[40:41], v[40:41], v[4:5] op_sel_hi:[1,0]
	v_pk_mul_f32 v[38:39], v[38:39], v[4:5] op_sel_hi:[1,0]
	v_pk_mul_f32 v[36:37], v[36:37], v[4:5] op_sel_hi:[1,0]
	v_pk_mul_f32 v[34:35], v[34:35], v[4:5] op_sel_hi:[1,0]
	v_pk_mul_f32 v[32:33], v[32:33], v[4:5] op_sel_hi:[1,0]
	v_pk_mul_f32 v[30:31], v[30:31], v[4:5] op_sel_hi:[1,0]
	v_pk_mul_f32 v[28:29], v[28:29], v[4:5] op_sel_hi:[1,0]
	v_pk_mul_f32 v[26:27], v[26:27], v[4:5] op_sel_hi:[1,0]
	v_pk_mul_f32 v[24:25], v[24:25], v[4:5] op_sel_hi:[1,0]
	v_pk_mul_f32 v[22:23], v[22:23], v[4:5] op_sel_hi:[1,0]
	v_pk_mul_f32 v[20:21], v[20:21], v[4:5] op_sel_hi:[1,0]
	v_pk_mul_f32 v[18:19], v[18:19], v[4:5] op_sel_hi:[1,0]
	v_pk_mul_f32 v[16:17], v[16:17], v[4:5] op_sel_hi:[1,0]
	v_pk_mul_f32 v[62:63], v[62:63], v[4:5] op_sel_hi:[1,0]
	v_pk_mul_f32 v[60:61], v[60:61], v[4:5] op_sel_hi:[1,0]
	v_pk_mul_f32 v[58:59], v[58:59], v[4:5] op_sel_hi:[1,0]
	v_pk_mul_f32 v[56:57], v[56:57], v[4:5] op_sel_hi:[1,0]
	v_pk_mul_f32 v[54:55], v[54:55], v[4:5] op_sel_hi:[1,0]
	v_pk_mul_f32 v[52:53], v[52:53], v[4:5] op_sel_hi:[1,0]
	v_pk_mul_f32 v[50:51], v[50:51], v[4:5] op_sel_hi:[1,0]
	v_pk_mul_f32 v[48:49], v[48:49], v[4:5] op_sel_hi:[1,0]
	v_pk_mul_f32 v[78:79], v[78:79], v[4:5] op_sel_hi:[1,0]
	v_pk_mul_f32 v[76:77], v[76:77], v[4:5] op_sel_hi:[1,0]
	v_pk_mul_f32 v[74:75], v[74:75], v[4:5] op_sel_hi:[1,0]
	v_pk_mul_f32 v[72:73], v[72:73], v[4:5] op_sel_hi:[1,0]
	v_pk_mul_f32 v[70:71], v[70:71], v[4:5] op_sel_hi:[1,0]
	v_pk_mul_f32 v[68:69], v[68:69], v[4:5] op_sel_hi:[1,0]
	v_pk_mul_f32 v[66:67], v[66:67], v[4:5] op_sel_hi:[1,0]
	v_pk_mul_f32 v[64:65], v[64:65], v[4:5] op_sel_hi:[1,0]
	v_pk_mul_f32 v[242:243], v[242:243], v[4:5] op_sel_hi:[1,0]
	v_pk_mul_f32 v[240:241], v[240:241], v[4:5] op_sel_hi:[1,0]
	v_sub_f32_e32 v80, 0, v153
	v_mov_b32_e32 v81, v80
	v_mov_b32_e32 v82, v80
	v_mov_b32_e32 v83, v80
	v_mov_b32_e32 v84, v80
	v_mov_b32_e32 v85, v80
	v_mov_b32_e32 v86, v80
	v_mov_b32_e32 v87, v80
	v_mov_b32_e32 v88, v80
	v_mov_b32_e32 v89, v80
	v_mov_b32_e32 v90, v80
	v_mov_b32_e32 v91, v80
	v_mov_b32_e32 v92, v80
	v_mov_b32_e32 v93, v80
	v_mov_b32_e32 v94, v80
	v_mov_b32_e32 v95, v80
; template <bool DIFF> ...
;     ...
; #pragma unroll
;             for (int ii = 0; ii < 16; ++ii) { s0[ii] = __builtin_amdgcn_exp2f(s0[ii]); s1[ii] = __builtin_amdgcn_exp2f(s1[ii]); }
;             pk[0][0] = pack8(s0, 0); pk[0][1] = pack8(s0, 8); pk[1][0] = pack8(s1, 0); pk[1][1] = pack8(s1, 8);
;         }
;         if (!late && active) A_PV(t & 3);
.LBB0_1492:
	v_exp_f32_e32 v0, v112
	v_exp_f32_e32 v10, v96
	v_exp_f32_e32 v2, v113
	v_exp_f32_e32 v11, v97
	v_exp_f32_e32 v3, v114
	v_exp_f32_e32 v12, v98
	v_exp_f32_e32 v4, v115
	v_exp_f32_e32 v13, v99
	v_exp_f32_e32 v5, v116
	v_exp_f32_e32 v14, v100
	v_exp_f32_e32 v6, v117
	v_exp_f32_e32 v15, v101
	v_exp_f32_e32 v7, v118
	v_exp_f32_e32 v96, v102
	v_exp_f32_e32 v8, v119
	v_exp_f32_e32 v97, v103
	v_exp_f32_e32 v9, v120
	v_exp_f32_e32 v98, v104
	v_exp_f32_e32 v99, v121
	v_exp_f32_e32 v100, v105
	v_exp_f32_e32 v101, v122
	v_exp_f32_e32 v102, v106
	v_exp_f32_e32 v103, v123
	v_exp_f32_e32 v104, v107
	v_exp_f32_e32 v105, v124
	v_exp_f32_e32 v106, v108
	v_exp_f32_e32 v107, v125
	v_exp_f32_e32 v108, v109
	v_exp_f32_e32 v109, v126
	v_exp_f32_e32 v110, v110
	v_exp_f32_e32 v112, v127
	v_exp_f32_e32 v111, v111
	v_add_f32_e32 v240, v240, v0
	v_add_f32_e32 v241, v241, v10
	v_add_f32_e32 v242, v242, v2
	v_add_f32_e32 v243, v243, v11
	v_add_f32_e32 v240, v240, v3
	v_add_f32_e32 v241, v241, v12
	v_add_f32_e32 v242, v242, v4
	v_add_f32_e32 v243, v243, v13
	v_add_f32_e32 v240, v240, v5
	v_add_f32_e32 v241, v241, v14
	v_add_f32_e32 v242, v242, v6
	v_add_f32_e32 v243, v243, v15
	v_add_f32_e32 v240, v240, v7
	v_add_f32_e32 v241, v241, v96
	v_add_f32_e32 v242, v242, v8
	v_add_f32_e32 v243, v243, v97
	v_add_f32_e32 v240, v240, v9
	v_add_f32_e32 v241, v241, v98
	v_add_f32_e32 v242, v242, v99
	v_add_f32_e32 v243, v243, v100
	v_add_f32_e32 v240, v240, v101
	v_add_f32_e32 v241, v241, v102
	v_add_f32_e32 v242, v242, v103
	v_add_f32_e32 v243, v243, v104
	v_add_f32_e32 v240, v240, v105
	v_add_f32_e32 v241, v241, v106
	v_add_f32_e32 v242, v242, v107
	v_add_f32_e32 v243, v243, v108
	v_add_f32_e32 v240, v240, v109
	v_add_f32_e32 v241, v241, v110
	v_add_f32_e32 v242, v242, v112
	v_add_f32_e32 v243, v243, v111
	v_cvt_pk_bf16_f32 v2, v0, v2
	v_cvt_pk_bf16_f32 v3, v3, v4
	v_cvt_pk_bf16_f32 v4, v5, v6
	v_cvt_pk_bf16_f32 v5, v7, v8
	v_cvt_pk_bf16_f32 v6, v9, v99
	v_cvt_pk_bf16_f32 v7, v101, v103
	v_cvt_pk_bf16_f32 v8, v105, v107
	v_cvt_pk_bf16_f32 v9, v109, v112
	v_cvt_pk_bf16_f32 v10, v10, v11
	v_cvt_pk_bf16_f32 v11, v12, v13
	v_cvt_pk_bf16_f32 v12, v14, v15
	v_cvt_pk_bf16_f32 v13, v96, v97
	v_cvt_pk_bf16_f32 v96, v98, v100
	v_cvt_pk_bf16_f32 v97, v102, v104
	v_cvt_pk_bf16_f32 v98, v106, v108
	v_cvt_pk_bf16_f32 v99, v110, v111
	s_mov_b64 s[12:13], 0
.LBB0_1493:
	s_andn2_b64 vcc, exec, s[78:79]
	s_cbranch_vccnz .LBB0_1495
	s_mulk_i32 s77, 0x5000
	v_add_u32_e32 v0, s77, v205
	ds_read_b64_tr_b16 v[100:101], v0 offset:52224
	ds_read_b64_tr_b16 v[102:103], v0 offset:54784
	ds_read_b64_tr_b16 v[104:105], v0 offset:52288
	ds_read_b64_tr_b16 v[108:109], v0 offset:52352
	ds_read_b64_tr_b16 v[112:113], v0 offset:52416
	ds_read_b64_tr_b16 v[106:107], v0 offset:54848
	ds_read_b64_tr_b16 v[110:111], v0 offset:54912
	ds_read_b64_tr_b16 v[114:115], v0 offset:54976
	s_waitcnt lgkmcnt(0)
	v_mfma_f32_32x32x16_bf16 v[32:47], v[100:103], v[2:5], v[32:47]
	ds_read_b64_tr_b16 v[118:119], v0 offset:59904
	ds_read_b64_tr_b16 v[116:117], v0 offset:57344
	ds_read_b64_tr_b16 v[120:121], v0 offset:57408
	ds_read_b64_tr_b16 v[124:125], v0 offset:57472
	ds_read_b64_tr_b16 v[212:213], v0 offset:57536
	ds_read_b64_tr_b16 v[122:123], v0 offset:59968
	ds_read_b64_tr_b16 v[126:127], v0 offset:60032
	ds_read_b64_tr_b16 v[214:215], v0 offset:60096
	v_mfma_f32_32x32x16_bf16 v[16:31], v[104:107], v[2:5], v[16:31]
	v_mfma_f32_32x32x16_bf16 v[48:63], v[108:111], v[2:5], v[48:63]
	v_mfma_f32_32x32x16_bf16 v[64:79], v[112:115], v[2:5], v[64:79]
	s_waitcnt lgkmcnt(0)
	v_mfma_f32_32x32x16_bf16 v[32:47], v[116:119], v[6:9], v[32:47]
	ds_read_b64_tr_b16 v[118:119], v0 offset:65024
	ds_read_b64_tr_b16 v[116:117], v0 offset:62464
	ds_read_b64_tr_b16 v[216:217], v0 offset:62528
	ds_read_b64_tr_b16 v[220:221], v0 offset:62592
	ds_read_b64_tr_b16 v[224:225], v0 offset:62656
	ds_read_b64_tr_b16 v[218:219], v0 offset:65088
	ds_read_b64_tr_b16 v[222:223], v0 offset:65152
	ds_read_b64_tr_b16 v[226:227], v0 offset:65216
	v_add_u32_e32 v0, 0xcc00, v0
	v_mfma_f32_32x32x16_bf16 v[16:31], v[120:123], v[6:9], v[16:31]
	v_mfma_f32_32x32x16_bf16 v[48:63], v[124:127], v[6:9], v[48:63]
	v_mfma_f32_32x32x16_bf16 v[64:79], v[212:215], v[6:9], v[64:79]
	s_waitcnt lgkmcnt(0)
	v_mfma_f32_32x32x16_bf16 v[32:47], v[116:119], v[10:13], v[32:47]
	ds_read_b64_tr_b16 v[118:119], v0 offset:17920
	ds_read_b64_tr_b16 v[116:117], v0 offset:15360
	ds_read_b64_tr_b16 v[228:229], v0 offset:15424
	ds_read_b64_tr_b16 v[232:233], v0 offset:15488
	ds_read_b64_tr_b16 v[236:237], v0 offset:15552
	ds_read_b64_tr_b16 v[230:231], v0 offset:17984
	ds_read_b64_tr_b16 v[234:235], v0 offset:18048
	ds_read_b64_tr_b16 v[238:239], v0 offset:18112
	v_mfma_f32_32x32x16_bf16 v[16:31], v[216:219], v[10:13], v[16:31]
	v_mfma_f32_32x32x16_bf16 v[48:63], v[220:223], v[10:13], v[48:63]
	v_mfma_f32_32x32x16_bf16 v[64:79], v[224:227], v[10:13], v[64:79]
	s_waitcnt lgkmcnt(0)
	v_mfma_f32_32x32x16_bf16 v[32:47], v[116:119], v[96:99], v[32:47]
	v_mfma_f32_32x32x16_bf16 v[16:31], v[228:231], v[96:99], v[16:31]
	v_mfma_f32_32x32x16_bf16 v[48:63], v[232:235], v[96:99], v[48:63]
	v_mfma_f32_32x32x16_bf16 v[64:79], v[236:239], v[96:99], v[64:79]

; template <bool DIFF> ...
;     ...
;     float l_ = lacc[0];
;     bool have = true;
;     if (split) {
;         if (h == 0) mb[wave * 32 + r] = m_;
;         __syncthreads();
;         float M = mb[mp * 32 + r];
; #pragma unroll
;         for (int g = 1; g < NG; ++g) M = fmaxf(M, mb[(g * NM + mp) * 32 + r]);
;         const float f = __builtin_amdgcn_exp2f(m_ - M);
;         l_ *= f;
;         if (h == 0) lb[wave * 32 + r] = l_;
; #pragma unroll
;         for (int db = 0; db < 4; ++db)
; #pragma unroll
;             for (int ii = 0; ii < 16; ++ii) red[(wave * 64 + db * 16 + ii) * 64 + lane] = O[db][ii] * f;
;         __syncthreads();
.LBB0_1498:
	v_add_f32_e32 v80, v240, v241
	v_add_f32_e32 v82, v242, v243
	v_add_f32_e32 v80, v80, v82
	v_mov_b32_e32 v81, v80
	s_nop 1
	v_permlane32_swap_b32_e32 v80, v81
	v_add_f32_e32 v80, v80, v81
	s_mov_b64 s[6:7], -1
	s_and_b64 vcc, exec, s[2:3]
	s_waitcnt vmcnt(0) lgkmcnt(0)
	s_barrier
	s_cbranch_vccz .LBB0_1506
	s_mov_b64 s[2:3], exec
	v_readlane_b32 s0, v255, 5
	v_readlane_b32 s1, v255, 6
	v_readlane_b32 s40, v255, 19
	v_readlane_b32 s20, v255, 21
	s_and_b64 s[0:1], s[2:3], s[0:1]
	v_readlane_b32 s41, v255, 20
	v_readlane_b32 s21, v255, 22
	v_readlane_b32 s14, v255, 23
	s_mov_b64 exec, s[0:1]
	v_lshl_add_u32 v0, s86, 7, v186
	ds_write_b32 v0, v153
	s_or_b64 exec, exec, s[2:3]
	v_add_u32_e32 v0, s94, v186
	s_waitcnt lgkmcnt(0)
	s_barrier
	ds_read2st64_b32 v[2:3], v0 offset1:1
	ds_read2st64_b32 v[4:5], v0 offset0:2 offset1:3
	s_waitcnt lgkmcnt(1)
	v_max_f32_e32 v0, v3, v3
	v_max_f32_e32 v2, v2, v2
	v_max_f32_e32 v0, v2, v0
	s_waitcnt lgkmcnt(0)
	v_max3_f32 v0, v0, v4, v5
	v_sub_f32_e32 v0, v153, v0
	v_exp_f32_e32 v2, v0
	v_lshl_add_u32 v0, s86, 7, v187
	v_mul_f32_e32 v80, v80, v2
	s_mov_b64 s[2:3], exec
	v_readlane_b32 s0, v255, 5
	v_readlane_b32 s1, v255, 6
	s_and_b64 s[0:1], s[2:3], s[0:1]
	s_mov_b64 exec, s[0:1]
	ds_write_b32 v0, v80
	s_or_b64 exec, exec, s[2:3]
	s_lshl_b32 s0, s89, 8
	s_and_b32 s1, s0, 0xffffc000
	v_mul_f32_e32 v3, v32, v2
	v_add_u32_e32 v4, s1, v184
	v_mul_f32_e32 v5, v33, v2
	ds_write2st64_b32 v4, v3, v5 offset1:1
	v_mul_f32_e32 v3, v34, v2
	v_mul_f32_e32 v5, v35, v2
	ds_write2st64_b32 v4, v3, v5 offset0:2 offset1:3
	v_mul_f32_e32 v3, v36, v2
	v_mul_f32_e32 v5, v37, v2
	ds_write2st64_b32 v4, v3, v5 offset0:4 offset1:5
	v_mul_f32_e32 v3, v38, v2
	v_mul_f32_e32 v5, v39, v2
	ds_write2st64_b32 v4, v3, v5 offset0:6 offset1:7
	v_mul_f32_e32 v3, v40, v2
	v_mul_f32_e32 v5, v41, v2
	ds_write2st64_b32 v4, v3, v5 offset0:8 offset1:9
	v_mul_f32_e32 v3, v42, v2
	v_mul_f32_e32 v5, v43, v2
	ds_write2st64_b32 v4, v3, v5 offset0:10 offset1:11
	v_mul_f32_e32 v3, v44, v2
	v_mul_f32_e32 v5, v45, v2
	ds_write2st64_b32 v4, v3, v5 offset0:12 offset1:13
	v_mul_f32_e32 v3, v46, v2
	v_mul_f32_e32 v5, v47, v2
	ds_write2st64_b32 v4, v3, v5 offset0:14 offset1:15
	v_mul_f32_e32 v3, v16, v2
	v_mul_f32_e32 v5, v17, v2
	ds_write2st64_b32 v4, v3, v5 offset0:16 offset1:17
	v_mul_f32_e32 v3, v18, v2
	v_mul_f32_e32 v5, v19, v2
	ds_write2st64_b32 v4, v3, v5 offset0:18 offset1:19
	v_mul_f32_e32 v3, v20, v2
	v_mul_f32_e32 v5, v21, v2
	ds_write2st64_b32 v4, v3, v5 offset0:20 offset1:21
	v_mul_f32_e32 v3, v22, v2
	v_mul_f32_e32 v5, v23, v2
	ds_write2st64_b32 v4, v3, v5 offset0:22 offset1:23
	v_mul_f32_e32 v3, v24, v2
	v_mul_f32_e32 v5, v25, v2
	ds_write2st64_b32 v4, v3, v5 offset0:24 offset1:25
	v_mul_f32_e32 v3, v26, v2
	v_mul_f32_e32 v5, v27, v2
	ds_write2st64_b32 v4, v3, v5 offset0:26 offset1:27
	v_mul_f32_e32 v3, v28, v2
	v_mul_f32_e32 v5, v29, v2
	ds_write2st64_b32 v4, v3, v5 offset0:28 offset1:29
	v_mul_f32_e32 v3, v30, v2
	v_mul_f32_e32 v5, v31, v2
	ds_write2st64_b32 v4, v3, v5 offset0:30 offset1:31
	v_mul_f32_e32 v3, v48, v2
	v_mul_f32_e32 v5, v49, v2
	ds_write2st64_b32 v4, v3, v5 offset0:32 offset1:33
	v_mul_f32_e32 v3, v50, v2
	v_mul_f32_e32 v5, v51, v2
	ds_write2st64_b32 v4, v3, v5 offset0:34 offset1:35
	v_mul_f32_e32 v3, v52, v2
	v_mul_f32_e32 v5, v53, v2
	ds_write2st64_b32 v4, v3, v5 offset0:36 offset1:37
	v_mul_f32_e32 v3, v54, v2
	v_mul_f32_e32 v5, v55, v2
	ds_write2st64_b32 v4, v3, v5 offset0:38 offset1:39
	v_mul_f32_e32 v3, v56, v2
	v_mul_f32_e32 v5, v57, v2
	ds_write2st64_b32 v4, v3, v5 offset0:40 offset1:41
	v_mul_f32_e32 v3, v58, v2
	v_mul_f32_e32 v5, v59, v2
	ds_write2st64_b32 v4, v3, v5 offset0:42 offset1:43
	v_mul_f32_e32 v3, v60, v2
	v_mul_f32_e32 v5, v61, v2
	ds_write2st64_b32 v4, v3, v5 offset0:44 offset1:45
	v_mul_f32_e32 v3, v62, v2
	v_mul_f32_e32 v5, v63, v2
	ds_write2st64_b32 v4, v3, v5 offset0:46 offset1:47
	v_mul_f32_e32 v3, v64, v2
	v_mul_f32_e32 v5, v65, v2
	ds_write2st64_b32 v4, v3, v5 offset0:48 offset1:49
	v_mul_f32_e32 v3, v66, v2
	v_mul_f32_e32 v5, v67, v2
	ds_write2st64_b32 v4, v3, v5 offset0:50 offset1:51
	v_mul_f32_e32 v3, v68, v2
	v_mul_f32_e32 v5, v69, v2
	ds_write2st64_b32 v4, v3, v5 offset0:52 offset1:53
	v_mul_f32_e32 v3, v70, v2
	v_mul_f32_e32 v5, v71, v2
	ds_write2st64_b32 v4, v3, v5 offset0:54 offset1:55
	v_mul_f32_e32 v3, v72, v2
	v_mul_f32_e32 v5, v73, v2
	ds_write2st64_b32 v4, v3, v5 offset0:56 offset1:57
	v_mul_f32_e32 v3, v74, v2
	v_mul_f32_e32 v5, v75, v2
	ds_write2st64_b32 v4, v3, v5 offset0:58 offset1:59
	v_mul_f32_e32 v3, v76, v2
	v_mul_f32_e32 v5, v77, v2
	s_cmpk_lt_u32 s89, 0x80
	ds_write2st64_b32 v4, v3, v5 offset0:60 offset1:61
	v_mul_f32_e32 v3, v78, v2
	v_mul_f32_e32 v2, v79, v2
	s_cselect_b64 s[6:7], -1, 0
	s_cmpk_gt_u32 s89, 0x7f
	ds_write2st64_b32 v4, v3, v2 offset0:62 offset1:63
	s_waitcnt lgkmcnt(0)
	s_barrier
	s_cbranch_scc1 .LBB0_1505
; template <bool DIFF> ...
;     ...
;         have = wave < NM;
;         if (have) {
; #pragma unroll
;             for (int db = 0; db < 4; ++db)
; #pragma unroll
;                 for (int ii = 0; ii < 16; ++ii) { float a = 0.f;
; #pragma unroll
;                     for (int g = 0; g < NG; ++g) a += red[((g * NM + mp) * 64 + db * 16 + ii) * 64 + lane];
;                     O[db][ii] = a; }
	s_and_b32 s1, s0, 0x4000
	s_or_b32 s2, s1, 0x100
	v_add_u32_e32 v8, s2, v188
	v_add_u32_e32 v9, s2, v189
	s_or_b32 s2, s1, 0x200
	v_add_u32_e32 v12, s2, v188
	v_add_u32_e32 v13, s2, v189
	s_or_b32 s2, s1, 0x300
	v_add_u32_e32 v14, s2, v188
	v_add_u32_e32 v15, s2, v189
	s_or_b32 s2, s1, 0x400
	v_add_u32_e32 v16, s2, v188
	v_add_u32_e32 v17, s2, v189
	s_or_b32 s2, s1, 0x500
	v_add_u32_e32 v18, s2, v188
	v_add_u32_e32 v19, s2, v189
	s_or_b32 s2, s1, 0x600
	v_add_u32_e32 v22, s2, v188
	v_add_u32_e32 v23, s2, v189
	s_or_b32 s2, s1, 0x700
	v_add_u32_e32 v24, s2, v188
	v_add_u32_e32 v25, s2, v189
	s_or_b32 s2, s1, 0x800
	v_add_u32_e32 v26, s2, v188
	v_add_u32_e32 v27, s2, v189
	s_or_b32 s2, s1, 0x900
	v_add_u32_e32 v28, s2, v188
	v_add_u32_e32 v29, s2, v189
	s_or_b32 s2, s1, 0xa00
	v_add_u32_e32 v70, s1, v184
	v_add_u32_e32 v6, s1, v188
	v_add_u32_e32 v7, s1, v189
	v_add_u32_e32 v32, s2, v188
	v_add_u32_e32 v33, s2, v189
	s_or_b32 s2, s1, 0xb00
	ds_read2st64_b32 v[2:3], v70 offset0:62 offset1:128
	ds_read2st64_b32 v[4:5], v70 offset0:129 offset1:130
	ds_read_b32 v10, v6
	ds_read_b32 v6, v7
	ds_read_b32 v11, v8
	ds_read_b32 v7, v9
	ds_read_b32 v12, v12
	ds_read_b32 v8, v13
	ds_read_b32 v13, v14
	ds_read_b32 v9, v15
	ds_read2st64_b32 v[14:15], v70 offset1:1
	ds_read2st64_b32 v[44:45], v70 offset0:2 offset1:3
	ds_read2st64_b32 v[46:47], v70 offset0:4 offset1:5
	ds_read2st64_b32 v[48:49], v70 offset0:6 offset1:7
	v_add_u32_e32 v34, s2, v188
	v_add_u32_e32 v35, s2, v189
	s_or_b32 s2, s1, 0xc00
	ds_read_b32 v20, v16
	ds_read_b32 v16, v17
	ds_read_b32 v21, v18
	ds_read_b32 v17, v19
	ds_read_b32 v22, v22
	ds_read_b32 v18, v23
	ds_read_b32 v23, v24
	ds_read_b32 v19, v25
	ds_read2st64_b32 v[24:25], v70 offset0:131 offset1:132
	ds_read2st64_b32 v[58:59], v70 offset0:133 offset1:134
	ds_read2st64_b32 v[56:57], v70 offset0:135 offset1:136
	ds_read2st64_b32 v[54:55], v70 offset0:137 offset1:138
	ds_read_b32 v30, v26
	ds_read_b32 v26, v27
	ds_read_b32 v31, v28
	ds_read_b32 v27, v29
	ds_read_b32 v32, v32
	ds_read_b32 v28, v33
	ds_read_b32 v33, v34
	ds_read_b32 v29, v35
	v_add_u32_e32 v34, s2, v188
	v_add_u32_e32 v35, s2, v189
	s_or_b32 s2, s1, 0xd00
	ds_read2st64_b32 v[50:51], v70 offset0:8 offset1:9
	ds_read2st64_b32 v[52:53], v70 offset0:10 offset1:11
	ds_read2st64_b32 v[60:61], v70 offset0:12 offset1:13
	ds_read2st64_b32 v[62:63], v70 offset0:14 offset1:15
	v_add_u32_e32 v37, s2, v188
	v_add_u32_e32 v38, s2, v189
	s_or_b32 s2, s1, 0xe00
	v_add_u32_e32 v39, s2, v188
	v_add_u32_e32 v41, s2, v189
	s_or_b32 s2, s1, 0xf00
	v_add_u32_e32 v42, s2, v188
	v_add_u32_e32 v43, s2, v189
	ds_read_b32 v36, v34
	ds_read_b32 v34, v35
	ds_read_b32 v37, v37
	ds_read_b32 v35, v38
	ds_read_b32 v40, v39
	ds_read_b32 v38, v41
	ds_read_b32 v41, v42
	ds_read_b32 v39, v43
	s_waitcnt lgkmcnt(14)
	v_pk_add_f32 v[42:43], v[14:15], 0 op_sel_hi:[1,0]
	v_pk_add_f32 v[66:67], v[48:49], 0 op_sel_hi:[1,0]
	s_waitcnt lgkmcnt(11)
	v_pk_add_f32 v[68:69], v[50:51], 0 op_sel_hi:[1,0]
	s_waitcnt lgkmcnt(9)
	v_pk_add_f32 v[50:51], v[60:61], 0 op_sel_hi:[1,0]
	ds_read2st64_b32 v[60:61], v70 offset0:141 offset1:142
	ds_read2st64_b32 v[14:15], v70 offset0:143 offset1:144
	ds_read2st64_b32 v[48:49], v70 offset0:145 offset1:146
	ds_read2st64_b32 v[72:73], v70 offset0:139 offset1:140
	v_pk_add_f32 v[64:65], v[46:47], 0 op_sel_hi:[1,0]
	s_waitcnt lgkmcnt(12)
	v_pk_add_f32 v[46:47], v[62:63], 0 op_sel_hi:[1,0]
	s_waitcnt lgkmcnt(3)
	v_mov_b32_e32 v62, v61
	s_waitcnt lgkmcnt(2)
	v_mov_b32_e32 v63, v14
	v_pk_add_f32 v[52:53], v[52:53], 0 op_sel_hi:[1,0]
	v_pk_add_f32 v[46:47], v[46:47], v[62:63]
	v_mov_b32_e32 v63, v60
	v_mov_b32_e32 v60, v55
	s_waitcnt lgkmcnt(0)
	v_mov_b32_e32 v61, v72
	v_pk_add_f32 v[52:53], v[52:53], v[60:61]
	v_mov_b32_e32 v60, v57
	v_mov_b32_e32 v61, v54
	v_pk_add_f32 v[54:55], v[68:69], v[60:61]
	v_mov_b32_e32 v60, v59
	v_mov_b32_e32 v61, v56
	v_pk_add_f32 v[56:57], v[66:67], v[60:61]
	v_mov_b32_e32 v60, v25
	v_mov_b32_e32 v61, v58
	v_pk_add_f32 v[44:45], v[44:45], 0 op_sel_hi:[1,0]
	v_pk_add_f32 v[58:59], v[64:65], v[60:61]
	v_mov_b32_e32 v60, v5
	v_mov_b32_e32 v61, v24
	v_pk_add_f32 v[24:25], v[44:45], v[60:61]
	v_mov_b32_e32 v44, v3
	v_mov_b32_e32 v45, v4
	v_mov_b32_e32 v62, v73
	v_pk_add_f32 v[4:5], v[42:43], v[44:45]
	v_pk_add_f32 v[50:51], v[50:51], v[62:63]
	v_pk_add_f32 v[4:5], v[4:5], v[10:11]
	v_pk_add_f32 v[10:11], v[24:25], v[12:13]
	v_pk_add_f32 v[24:25], v[52:53], v[32:33]
	v_pk_add_f32 v[32:33], v[46:47], v[40:41]
	s_or_b32 s2, s1, 0x1000
	v_pk_add_f32 v[12:13], v[58:59], v[20:21]
	v_pk_add_f32 v[20:21], v[56:57], v[22:23]
	v_pk_add_f32 v[22:23], v[54:55], v[30:31]
	v_pk_add_f32 v[30:31], v[50:51], v[36:37]
	v_pk_add_f32 v[46:47], v[32:33], v[38:39]
	v_pk_add_f32 v[32:33], v[4:5], v[6:7]
	v_add_u32_e32 v3, s2, v188
	v_add_u32_e32 v5, s2, v189
	s_or_b32 s2, s1, 0x1100
	v_pk_add_f32 v[44:45], v[30:31], v[34:35]
	v_pk_add_f32 v[34:35], v[10:11], v[8:9]
	v_add_u32_e32 v7, s2, v188
	v_add_u32_e32 v8, s2, v189
	s_or_b32 s2, s1, 0x1200
	v_add_u32_e32 v9, s2, v188
	v_add_u32_e32 v10, s2, v189
	s_or_b32 s2, s1, 0x1300
	v_pk_add_f32 v[36:37], v[12:13], v[16:17]
	v_add_u32_e32 v11, s2, v188
	v_add_u32_e32 v12, s2, v189
	s_or_b32 s2, s1, 0x1400
	ds_read2st64_b32 v[64:65], v70 offset0:56 offset1:57
	ds_read2st64_b32 v[66:67], v70 offset0:58 offset1:59
	ds_read2st64_b32 v[68:69], v70 offset0:60 offset1:61
	ds_read_b32 v4, v3
	ds_read_b32 v6, v5
	ds_read_b32 v5, v7
	ds_read_b32 v7, v8
	ds_read_b32 v8, v9
	ds_read_b32 v10, v10
	ds_read_b32 v9, v11
	ds_read_b32 v11, v12
	v_add_u32_e32 v3, s2, v188
	v_add_u32_e32 v14, s2, v189
	s_or_b32 s2, s1, 0x1500
	v_pk_add_f32 v[42:43], v[24:25], v[28:29]
; template <bool DIFF> ...
;     ...
;         have = wave < NM;
;         if (have) {
; #pragma unroll
;             for (int db = 0; db < 4; ++db)
; #pragma unroll
;                 for (int ii = 0; ii < 16; ++ii) { float a = 0.f;
; #pragma unroll
;                     for (int g = 0; g < NG; ++g) a += red[((g * NM + mp) * 64 + db * 16 + ii) * 64 + lane];
;                     O[db][ii] = a; }
	v_pk_add_f32 v[40:41], v[22:23], v[26:27]
	v_add_u32_e32 v23, s2, v188
	v_add_u32_e32 v24, s2, v189
	s_or_b32 s2, s1, 0x1600
	v_add_u32_e32 v25, s2, v188
	v_add_u32_e32 v26, s2, v189
	s_or_b32 s2, s1, 0x1700
	v_add_u32_e32 v27, s2, v188
	v_add_u32_e32 v28, s2, v189
	s_or_b32 s2, s1, 0x1800
	v_pk_add_f32 v[38:39], v[20:21], v[18:19]
	ds_read2st64_b32 v[12:13], v70 offset0:16 offset1:17
	ds_read2st64_b32 v[16:17], v70 offset0:18 offset1:19
	ds_read2st64_b32 v[18:19], v70 offset0:20 offset1:21
	ds_read2st64_b32 v[20:21], v70 offset0:22 offset1:23
	ds_read_b32 v22, v3
	ds_read_b32 v50, v14
	ds_read_b32 v23, v23
	ds_read_b32 v51, v24
	ds_read_b32 v24, v25
	ds_read_b32 v52, v26
	ds_read_b32 v25, v27
	ds_read_b32 v53, v28
	v_add_u32_e32 v3, s2, v188
	v_add_u32_e32 v14, s2, v189
	s_or_b32 s2, s1, 0x1900
	v_add_u32_e32 v57, s2, v188
	v_add_u32_e32 v59, s2, v189
	s_or_b32 s2, s1, 0x1a00
	v_add_u32_e32 v60, s2, v188
	v_add_u32_e32 v61, s2, v189
	s_or_b32 s2, s1, 0x1b00
	v_add_u32_e32 v63, s2, v188
	v_add_u32_e32 v71, s2, v189
	s_or_b32 s2, s1, 0x1c00
	ds_read2st64_b32 v[26:27], v70 offset0:147 offset1:148
	ds_read2st64_b32 v[28:29], v70 offset0:149 offset1:150
	ds_read2st64_b32 v[30:31], v70 offset0:151 offset1:152
	ds_read2st64_b32 v[54:55], v70 offset0:153 offset1:154
	ds_read_b32 v56, v3
	ds_read_b32 v58, v14
	ds_read_b32 v57, v57
	ds_read_b32 v59, v59
	ds_read_b32 v60, v60
	ds_read_b32 v62, v61
	ds_read_b32 v61, v63
	ds_read_b32 v63, v71
	v_add_u32_e32 v3, s2, v188
	v_add_u32_e32 v14, s2, v189
	s_or_b32 s2, s1, 0x1d00
	v_add_u32_e32 v71, s2, v188
	v_add_u32_e32 v83, s2, v189
	s_or_b32 s2, s1, 0x1e00
	v_add_u32_e32 v84, s2, v188
	v_add_u32_e32 v85, s2, v189
	s_or_b32 s2, s1, 0x1f00
	ds_read2st64_b32 v[72:73], v70 offset0:24 offset1:25
	ds_read2st64_b32 v[74:75], v70 offset0:26 offset1:27
	ds_read2st64_b32 v[76:77], v70 offset0:28 offset1:29
	ds_read2st64_b32 v[78:79], v70 offset0:30 offset1:31
	v_add_u32_e32 v87, s2, v188
	v_add_u32_e32 v88, s2, v189
	ds_read_b32 v80, v3
	ds_read_b32 v82, v14
	ds_read_b32 v81, v71
	ds_read_b32 v83, v83
	ds_read_b32 v84, v84
	ds_read_b32 v86, v85
	ds_read_b32 v85, v87
	ds_read_b32 v87, v88
	ds_read2st64_b32 v[88:89], v70 offset0:157 offset1:158
	ds_read2st64_b32 v[90:91], v70 offset0:159 offset1:160
	ds_read2st64_b32 v[92:93], v70 offset0:161 offset1:162
	ds_read2st64_b32 v[94:95], v70 offset0:155 offset1:156
	s_waitcnt lgkmcnt(12)
	v_pk_add_f32 v[78:79], v[78:79], 0 op_sel_hi:[1,0]
	s_waitcnt lgkmcnt(3)
	v_mov_b32_e32 v96, v89
	s_waitcnt lgkmcnt(2)
	v_mov_b32_e32 v97, v90
	v_pk_add_f32 v[74:75], v[74:75], 0 op_sel_hi:[1,0]
	v_pk_add_f32 v[78:79], v[78:79], v[96:97]
	v_mov_b32_e32 v97, v88
	v_mov_b32_e32 v88, v55
	s_waitcnt lgkmcnt(0)
	v_mov_b32_e32 v89, v94
	v_pk_add_f32 v[72:73], v[72:73], 0 op_sel_hi:[1,0]
	v_pk_add_f32 v[74:75], v[74:75], v[88:89]
	v_mov_b32_e32 v88, v31
	v_mov_b32_e32 v89, v54
	v_pk_add_f32 v[12:13], v[12:13], 0 op_sel_hi:[1,0]
	v_pk_add_f32 v[16:17], v[16:17], 0 op_sel_hi:[1,0]
	v_pk_add_f32 v[54:55], v[72:73], v[88:89]
	v_mov_b32_e32 v72, v29
	v_mov_b32_e32 v31, v28
	v_mov_b32_e32 v28, v49
	v_mov_b32_e32 v29, v26
	v_mov_b32_e32 v14, v15
	v_mov_b32_e32 v15, v48
	v_pk_add_f32 v[18:19], v[18:19], 0 op_sel_hi:[1,0]
	v_pk_add_f32 v[20:21], v[20:21], 0 op_sel_hi:[1,0]
	v_mov_b32_e32 v73, v30
	v_mov_b32_e32 v30, v27
	v_pk_add_f32 v[16:17], v[16:17], v[28:29]
	v_pk_add_f32 v[12:13], v[12:13], v[14:15]
	v_pk_add_f32 v[20:21], v[20:21], v[72:73]
	v_pk_add_f32 v[18:19], v[18:19], v[30:31]
	v_pk_add_f32 v[4:5], v[12:13], v[4:5]
	v_pk_add_f32 v[8:9], v[16:17], v[8:9]
	v_pk_add_f32 v[16:17], v[54:55], v[56:57]
	s_or_b32 s2, s1, 0x2000
	v_pk_add_f32 v[76:77], v[76:77], 0 op_sel_hi:[1,0]
	v_mov_b32_e32 v96, v95
	v_pk_add_f32 v[12:13], v[18:19], v[22:23]
	v_pk_add_f32 v[14:15], v[20:21], v[24:25]
	v_pk_add_f32 v[18:19], v[74:75], v[60:61]
	v_pk_add_f32 v[24:25], v[16:17], v[58:59]
	v_pk_add_f32 v[16:17], v[4:5], v[6:7]
	v_add_u32_e32 v3, s2, v188
	v_add_u32_e32 v5, s2, v189
	s_or_b32 s2, s1, 0x2100
	v_pk_add_f32 v[76:77], v[76:77], v[96:97]
	v_pk_add_f32 v[26:27], v[18:19], v[62:63]
	v_pk_add_f32 v[18:19], v[8:9], v[10:11]
	v_add_u32_e32 v7, s2, v188
	v_add_u32_e32 v8, s2, v189
	s_or_b32 s2, s1, 0x2200
	v_pk_add_f32 v[20:21], v[76:77], v[80:81]
	v_add_u32_e32 v9, s2, v188
	v_add_u32_e32 v10, s2, v189
	s_or_b32 s2, s1, 0x2300
	v_pk_add_f32 v[22:23], v[78:79], v[84:85]
	v_pk_add_f32 v[28:29], v[20:21], v[82:83]
	v_pk_add_f32 v[20:21], v[12:13], v[50:51]
	v_add_u32_e32 v11, s2, v188
	v_add_u32_e32 v12, s2, v189
	s_or_b32 s2, s1, 0x2400
	v_pk_add_f32 v[30:31], v[22:23], v[86:87]
	v_pk_add_f32 v[22:23], v[14:15], v[52:53]
	ds_read_b32 v4, v3
	ds_read_b32 v6, v5
	ds_read_b32 v5, v7
	ds_read_b32 v7, v8
	ds_read_b32 v8, v9
	ds_read_b32 v10, v10
	ds_read_b32 v9, v11
	ds_read_b32 v11, v12
	v_add_u32_e32 v3, s2, v188
	v_add_u32_e32 v53, s2, v189
	s_or_b32 s2, s1, 0x2500
	v_add_u32_e32 v54, s2, v188
	v_add_u32_e32 v55, s2, v189
	s_or_b32 s2, s1, 0x2600
	v_add_u32_e32 v56, s2, v188
	v_add_u32_e32 v57, s2, v189
	s_or_b32 s2, s1, 0x2700
	v_add_u32_e32 v58, s2, v188
	v_add_u32_e32 v59, s2, v189
	s_or_b32 s2, s1, 0x2800
	ds_read2st64_b32 v[12:13], v70 offset0:32 offset1:33
	ds_read2st64_b32 v[14:15], v70 offset0:34 offset1:35
	ds_read2st64_b32 v[48:49], v70 offset0:36 offset1:37
	ds_read2st64_b32 v[50:51], v70 offset0:38 offset1:39
	ds_read_b32 v52, v3
	ds_read_b32 v72, v53
	ds_read_b32 v53, v54
	ds_read_b32 v73, v55
	ds_read_b32 v54, v56
	ds_read_b32 v74, v57
	ds_read_b32 v55, v58
	ds_read_b32 v75, v59
	v_add_u32_e32 v3, s2, v188
	v_add_u32_e32 v71, s2, v189
	s_or_b32 s2, s1, 0x2900
	v_add_u32_e32 v77, s2, v188
; template <bool DIFF> ...
;     ...
;         have = wave < NM;
;         if (have) {
; #pragma unroll
;             for (int db = 0; db < 4; ++db)
; #pragma unroll
;                 for (int ii = 0; ii < 16; ++ii) { float a = 0.f;
; #pragma unroll
;                     for (int g = 0; g < NG; ++g) a += red[((g * NM + mp) * 64 + db * 16 + ii) * 64 + lane];
;                     O[db][ii] = a; }
	v_add_u32_e32 v79, s2, v189
	s_or_b32 s2, s1, 0x2a00
	v_add_u32_e32 v80, s2, v188
	v_add_u32_e32 v81, s2, v189
	s_or_b32 s2, s1, 0x2b00
	v_add_u32_e32 v83, s2, v188
	v_add_u32_e32 v84, s2, v189
	s_or_b32 s2, s1, 0x2c00
	ds_read2st64_b32 v[56:57], v70 offset0:163 offset1:164
	ds_read2st64_b32 v[58:59], v70 offset0:165 offset1:166
	ds_read2st64_b32 v[60:61], v70 offset0:167 offset1:168
	ds_read2st64_b32 v[62:63], v70 offset0:169 offset1:170
	ds_read_b32 v76, v3
	ds_read_b32 v78, v71
	ds_read_b32 v77, v77
	ds_read_b32 v79, v79
	ds_read_b32 v80, v80
	ds_read_b32 v82, v81
	ds_read_b32 v81, v83
	ds_read_b32 v83, v84
	v_add_u32_e32 v3, s2, v188
	v_add_u32_e32 v71, s2, v189
	s_or_b32 s2, s1, 0x2d00
	v_add_u32_e32 v90, s2, v188
	v_add_u32_e32 v99, s2, v189
	s_or_b32 s2, s1, 0x2e00
	v_add_u32_e32 v100, s2, v188
	v_add_u32_e32 v101, s2, v189
	s_or_b32 s2, s1, 0x2f00
	ds_read2st64_b32 v[84:85], v70 offset0:40 offset1:41
	ds_read2st64_b32 v[86:87], v70 offset0:42 offset1:43
	ds_read2st64_b32 v[88:89], v70 offset0:44 offset1:45
	ds_read2st64_b32 v[94:95], v70 offset0:46 offset1:47
	v_add_u32_e32 v103, s2, v188
	v_add_u32_e32 v104, s2, v189
	ds_read_b32 v96, v3
	ds_read_b32 v98, v71
	ds_read_b32 v97, v90
	ds_read_b32 v99, v99
	ds_read_b32 v100, v100
	ds_read_b32 v102, v101
	ds_read_b32 v101, v103
	ds_read_b32 v103, v104
	ds_read2st64_b32 v[104:105], v70 offset0:173 offset1:174
	ds_read2st64_b32 v[106:107], v70 offset0:175 offset1:176
	ds_read2st64_b32 v[108:109], v70 offset0:177 offset1:178
	ds_read2st64_b32 v[110:111], v70 offset0:171 offset1:172
	s_waitcnt lgkmcnt(12)
	v_pk_add_f32 v[94:95], v[94:95], 0 op_sel_hi:[1,0]
	s_waitcnt lgkmcnt(3)
	v_mov_b32_e32 v112, v105
	s_waitcnt lgkmcnt(2)
	v_mov_b32_e32 v113, v106
	v_pk_add_f32 v[86:87], v[86:87], 0 op_sel_hi:[1,0]
	v_pk_add_f32 v[94:95], v[94:95], v[112:113]
	v_mov_b32_e32 v113, v104
	v_mov_b32_e32 v104, v63
	s_waitcnt lgkmcnt(0)
	v_mov_b32_e32 v105, v110
	v_pk_add_f32 v[84:85], v[84:85], 0 op_sel_hi:[1,0]
	v_pk_add_f32 v[86:87], v[86:87], v[104:105]
	v_mov_b32_e32 v104, v61
	v_mov_b32_e32 v105, v62
	v_pk_add_f32 v[12:13], v[12:13], 0 op_sel_hi:[1,0]
	v_pk_add_f32 v[48:49], v[48:49], 0 op_sel_hi:[1,0]
	v_pk_add_f32 v[62:63], v[84:85], v[104:105]
	v_mov_b32_e32 v84, v59
	v_mov_b32_e32 v85, v60
	v_mov_b32_e32 v60, v57
	v_mov_b32_e32 v61, v58
	v_mov_b32_e32 v59, v56
	v_mov_b32_e32 v56, v91
	v_mov_b32_e32 v57, v92
	v_pk_add_f32 v[14:15], v[14:15], 0 op_sel_hi:[1,0]
	v_pk_add_f32 v[50:51], v[50:51], 0 op_sel_hi:[1,0]
	v_pk_add_f32 v[48:49], v[48:49], v[60:61]
	v_mov_b32_e32 v58, v93
	v_pk_add_f32 v[12:13], v[12:13], v[56:57]
	v_pk_add_f32 v[50:51], v[50:51], v[84:85]
	v_pk_add_f32 v[14:15], v[14:15], v[58:59]
	v_pk_add_f32 v[4:5], v[12:13], v[4:5]
	v_pk_add_f32 v[12:13], v[48:49], v[52:53]
	v_pk_add_f32 v[48:49], v[62:63], v[76:77]
	s_or_b32 s2, s1, 0x3000
	v_pk_add_f32 v[88:89], v[88:89], 0 op_sel_hi:[1,0]
	v_mov_b32_e32 v112, v111
	v_pk_add_f32 v[8:9], v[14:15], v[8:9]
	v_pk_add_f32 v[14:15], v[50:51], v[54:55]
	v_pk_add_f32 v[50:51], v[86:87], v[80:81]
	v_pk_add_f32 v[56:57], v[48:49], v[78:79]
	v_pk_add_f32 v[48:49], v[4:5], v[6:7]
	v_add_u32_e32 v3, s2, v188
	v_add_u32_e32 v5, s2, v189
	s_or_b32 s2, s1, 0x3100
	v_pk_add_f32 v[88:89], v[88:89], v[112:113]
	v_pk_add_f32 v[58:59], v[50:51], v[82:83]
	v_pk_add_f32 v[50:51], v[8:9], v[10:11]
	v_add_u32_e32 v7, s2, v188
	v_add_u32_e32 v8, s2, v189
	s_or_b32 s2, s1, 0x3200
	v_pk_add_f32 v[52:53], v[88:89], v[96:97]
	v_add_u32_e32 v9, s2, v188
	v_add_u32_e32 v10, s2, v189
	s_or_b32 s2, s1, 0x3300
	v_pk_add_f32 v[60:61], v[52:53], v[98:99]
	v_pk_add_f32 v[52:53], v[12:13], v[72:73]
	v_add_u32_e32 v11, s2, v188
	v_add_u32_e32 v12, s2, v189
	s_or_b32 s2, s1, 0x3400
	ds_read_b32 v4, v3
	ds_read_b32 v6, v5
	ds_read_b32 v5, v7
	ds_read_b32 v7, v8
	ds_read_b32 v8, v9
	ds_read_b32 v10, v10
	ds_read_b32 v9, v11
	ds_read_b32 v11, v12
	v_add_u32_e32 v3, s2, v188
	v_add_u32_e32 v71, s2, v189
	s_or_b32 s2, s1, 0x3500
	v_add_u32_e32 v77, s2, v188
	v_add_u32_e32 v78, s2, v189
	s_or_b32 s2, s1, 0x3600
	v_add_u32_e32 v79, s2, v188
	v_add_u32_e32 v82, s2, v189
	s_or_b32 s2, s1, 0x3700
	v_pk_add_f32 v[54:55], v[94:95], v[100:101]
	v_add_u32_e32 v83, s2, v188
	v_add_u32_e32 v84, s2, v189
	s_or_b32 s2, s1, 0x3800
	v_pk_add_f32 v[62:63], v[54:55], v[102:103]
	v_pk_add_f32 v[54:55], v[14:15], v[74:75]
	ds_read2st64_b32 v[12:13], v70 offset0:48 offset1:49
	ds_read2st64_b32 v[14:15], v70 offset0:50 offset1:51
	ds_read2st64_b32 v[72:73], v70 offset0:52 offset1:53
	ds_read2st64_b32 v[74:75], v70 offset0:54 offset1:55
	ds_read_b32 v76, v3
	ds_read_b32 v80, v71
	ds_read_b32 v77, v77
	ds_read_b32 v81, v78
	ds_read_b32 v78, v79
	ds_read_b32 v82, v82
	ds_read_b32 v79, v83
	ds_read_b32 v83, v84
	v_add_u32_e32 v3, s2, v188
	v_add_u32_e32 v71, s2, v189
	s_or_b32 s2, s1, 0x3900
	v_add_u32_e32 v93, s2, v188
	v_add_u32_e32 v95, s2, v189
	s_or_b32 s2, s1, 0x3a00
	v_add_u32_e32 v96, s2, v188
	v_add_u32_e32 v97, s2, v189
	s_or_b32 s2, s1, 0x3b00
	s_or_b32 s0, s0, 0x3f00
	v_add_u32_e32 v99, s2, v188
	v_add_u32_e32 v100, s2, v189
	v_add_u32_e32 v102, s0, v184
	ds_read2st64_b32 v[84:85], v70 offset0:179 offset1:180
	ds_read2st64_b32 v[86:87], v70 offset0:181 offset1:182
	ds_read2st64_b32 v[88:89], v70 offset0:183 offset1:184
	ds_read2st64_b32 v[90:91], v70 offset0:185 offset1:186
	ds_read_b32 v92, v3
	ds_read_b32 v94, v71
	ds_read_b32 v93, v93
	ds_read_b32 v95, v95
	ds_read_b32 v96, v96
	ds_read_b32 v98, v97
	ds_read_b32 v97, v99
	ds_read_b32 v99, v100
	ds_read2st64_b32 v[100:101], v70 offset0:187 offset1:188
	ds_read2st64_b32 v[70:71], v70 offset0:189 offset1:190
	ds_read2st64_b32 v[102:103], v102 offset1:128
	s_or_b32 s2, s1, 0x3c00
	v_add_u32_e32 v3, s2, v188
	v_add_u32_e32 v105, s2, v189
	s_or_b32 s2, s1, 0x3d00
	s_or_b32 s1, s1, 0x3e00
	v_add_u32_e32 v111, s2, v189
	v_add_u32_e32 v112, s1, v188
	v_add_u32_e32 v113, s1, v189
	v_add_u32_e32 v115, s0, v188
	v_add_u32_e32 v106, s2, v188
	v_add_u32_e32 v116, s0, v189
	ds_read_b32 v104, v3
	ds_read_b32 v110, v105
	ds_read_b32 v105, v106
	ds_read_b32 v111, v111
	ds_read_b32 v112, v112
	ds_read_b32 v114, v113
	ds_read_b32 v113, v115
	ds_read_b32 v115, v116
	s_waitcnt lgkmcnt(8)
; template <bool DIFF> ...
;     ...
; #pragma unroll
;             for (int db = 0; db < 4; ++db)
; #pragma unroll
;                 for (int ii = 0; ii < 16; ++ii) { float a = 0.f;
; #pragma unroll
;                     for (int g = 0; g < NG; ++g) a += red[((g * NM + mp) * 64 + db * 16 + ii) * 64 + lane];
;                     O[db][ii] = a; }
;             float lt = 0.f;
; #pragma unroll
;             for (int g = 0; g < NG; ++g) lt += lb[(g * NM + mp) * 32 + r];
;             l_ = lt;
	v_mov_b32_e32 v3, v102
	v_pk_add_f32 v[2:3], v[2:3], 0 op_sel_hi:[1,0]
	v_mov_b32_e32 v102, v71
	v_pk_add_f32 v[66:67], v[66:67], 0 op_sel_hi:[1,0]
	v_pk_add_f32 v[2:3], v[2:3], v[102:103]
	v_mov_b32_e32 v103, v70
	v_mov_b32_e32 v70, v91
	v_mov_b32_e32 v71, v100
	v_pk_add_f32 v[64:65], v[64:65], 0 op_sel_hi:[1,0]
	v_pk_add_f32 v[66:67], v[66:67], v[70:71]
	v_mov_b32_e32 v70, v89
	v_mov_b32_e32 v71, v90
	v_pk_add_f32 v[74:75], v[74:75], 0 op_sel_hi:[1,0]
	v_pk_add_f32 v[64:65], v[64:65], v[70:71]
	v_mov_b32_e32 v70, v87
	v_mov_b32_e32 v71, v88
	v_pk_add_f32 v[72:73], v[72:73], 0 op_sel_hi:[1,0]
	v_pk_add_f32 v[70:71], v[74:75], v[70:71]
	v_mov_b32_e32 v74, v85
	v_mov_b32_e32 v75, v86
	v_pk_add_f32 v[14:15], v[14:15], 0 op_sel_hi:[1,0]
	v_pk_add_f32 v[72:73], v[72:73], v[74:75]
	v_mov_b32_e32 v74, v109
	v_mov_b32_e32 v75, v84
	v_pk_add_f32 v[12:13], v[12:13], 0 op_sel_hi:[1,0]
	v_pk_add_f32 v[68:69], v[68:69], 0 op_sel_hi:[1,0]
	v_mov_b32_e32 v102, v101
	v_pk_add_f32 v[14:15], v[14:15], v[74:75]
	v_mov_b32_e32 v74, v107
	v_mov_b32_e32 v75, v108
	s_waitcnt lgkmcnt(1)
	v_pk_add_f32 v[2:3], v[2:3], v[112:113]
	v_pk_add_f32 v[68:69], v[68:69], v[102:103]
	v_pk_add_f32 v[12:13], v[12:13], v[74:75]
	v_pk_add_f32 v[8:9], v[14:15], v[8:9]
	v_pk_add_f32 v[14:15], v[70:71], v[78:79]
	s_waitcnt lgkmcnt(0)
	v_pk_add_f32 v[78:79], v[2:3], v[114:115]
	ds_read2st64_b32 v[2:3], v0 offset1:1
	v_pk_add_f32 v[4:5], v[12:13], v[4:5]
	v_pk_add_f32 v[12:13], v[72:73], v[76:77]
	v_pk_add_f32 v[68:69], v[68:69], v[104:105]
	v_pk_add_f32 v[64:65], v[64:65], v[92:93]
	v_pk_add_f32 v[76:77], v[68:69], v[110:111]
	v_pk_add_f32 v[68:69], v[12:13], v[80:81]
	ds_read2st64_b32 v[12:13], v0 offset0:2 offset1:3
	s_waitcnt lgkmcnt(1)
	v_add_f32_e32 v0, 0, v2
	v_add_f32_e32 v0, v0, v3
	v_pk_add_f32 v[66:67], v[66:67], v[96:97]
	v_pk_add_f32 v[72:73], v[64:65], v[94:95]
	s_waitcnt lgkmcnt(0)
	v_add_f32_e32 v0, v0, v12
	v_pk_add_f32 v[74:75], v[66:67], v[98:99]
	v_pk_add_f32 v[70:71], v[14:15], v[82:83]
	v_pk_add_f32 v[66:67], v[8:9], v[10:11]
	v_pk_add_f32 v[64:65], v[4:5], v[6:7]
	v_add_f32_e32 v80, v0, v13

; __device__ __forceinline__ u32x4 pack8f(const f32x4& a, const f32x4& b) { u32x4 w; w.x = ::pk2(a[0], a[1]); w.y = ::pk2(a[2], a[3]); w.z = ::pk2(b[0], b[1]); w.w = ::pk2(b[2], b[3]); return w; }
;     __device__ __forceinline__ void operator()(const f32x4 (&acc)[2][2][4][2], const Unit& u, int wr, int wc, int fr, int fq) const {
;     ...
;                 const int row = u.pm * BM + ai * HALF + wr * 64 + m * 16 + fr;
;                 const f32x4* sp = (const f32x4*)(ssq + (size_t)row * 16);
;                 const f32x4 a = sp[0] + sp[1] + sp[2] + sp[3];
;                 const float rstd = __builtin_amdgcn_rsqf(((a[0] + a[1]) + (a[2] + a[3])) * (1.0f / DM) + EPS) * scale;
; #pragma unroll
;                 for (int bj = 0; bj < 2; ++bj) {
;                     const int c = pn * BM + bj * HALF + cl;
;                     f32x4 v0 = acc[ai][bj][m][0] * rstd, v1 = acc[ai][bj][m][1] * rstd;
;                     if (ACT == 1) {
; #pragma unroll
;                         for (int e = 0; e < 4; ++e) { const float a0 = fmaxf(v0[e], 0.f), a1 = fmaxf(v1[e], 0.f); v0[e] = a0 * a0; v1[e] = a1 * a1; }
;                     }
;                     *(u32x4*)(O + (size_t)row * ldc + c) = pack8f(v0, v1);
.LBB0_1720:
	v_lshl_add_u32 v146, s22, 8, v148
	v_and_b32_e32 v147, 48, v206
	v_lshl_add_u32 v144, v146, 6, v147
	v_add_u32_e32 v145, 0x2000, v144
	global_load_dwordx4 v[178:181], v144, s[8:9]
	global_load_dwordx4 v[182:185], v144, s[8:9] offset:1024
	global_load_dwordx4 v[186:189], v144, s[8:9] offset:2048
	global_load_dwordx4 v[190:193], v144, s[8:9] offset:3072
	global_load_dwordx4 v[194:197], v145, s[8:9]
	global_load_dwordx4 v[198:201], v145, s[8:9] offset:1024
	global_load_dwordx4 v[202:205], v145, s[8:9] offset:2048
	global_load_dwordx4 v[208:211], v145, s[8:9] offset:3072
	v_lshl_or_b32 v172, s46, 8, v150
	v_lshlrev_b32_e32 v172, 1, v172
	v_lshl_add_u32 v172, v146, 13, v172
	s_waitcnt vmcnt(7)
	v_add_f32_e32 v212, v178, v179
	v_add_f32_e32 v213, v180, v181
	v_add_f32_e32 v212, v212, v213
	s_waitcnt vmcnt(6)
	v_add_f32_e32 v214, v182, v183
	v_add_f32_e32 v215, v184, v185
	v_add_f32_e32 v214, v214, v215
	s_waitcnt vmcnt(5)
	v_add_f32_e32 v216, v186, v187
	v_add_f32_e32 v217, v188, v189
	v_add_f32_e32 v216, v216, v217
	s_waitcnt vmcnt(4)
	v_add_f32_e32 v218, v190, v191
	v_add_f32_e32 v219, v192, v193
	v_add_f32_e32 v218, v218, v219
	s_waitcnt vmcnt(3)
	v_add_f32_e32 v220, v194, v195
	v_add_f32_e32 v221, v196, v197
	v_add_f32_e32 v220, v220, v221
	s_waitcnt vmcnt(2)
	v_add_f32_e32 v222, v198, v199
	v_add_f32_e32 v223, v200, v201
	v_add_f32_e32 v222, v222, v223
	s_waitcnt vmcnt(1)
	v_add_f32_e32 v224, v202, v203
	v_add_f32_e32 v225, v204, v205
	v_add_f32_e32 v224, v224, v225
	s_waitcnt vmcnt(0)
	v_add_f32_e32 v226, v208, v209
	v_add_f32_e32 v227, v210, v211
	v_add_f32_e32 v226, v226, v227
	ds_swizzle_b32 v213, v212 offset:swizzle(SWAP,16)
	ds_swizzle_b32 v215, v214 offset:swizzle(SWAP,16)
	ds_swizzle_b32 v217, v216 offset:swizzle(SWAP,16)
	ds_swizzle_b32 v219, v218 offset:swizzle(SWAP,16)
	ds_swizzle_b32 v221, v220 offset:swizzle(SWAP,16)
	ds_swizzle_b32 v223, v222 offset:swizzle(SWAP,16)
	ds_swizzle_b32 v225, v224 offset:swizzle(SWAP,16)
	ds_swizzle_b32 v227, v226 offset:swizzle(SWAP,16)
	s_waitcnt lgkmcnt(0)
	v_add_f32_e32 v212, v212, v213
	v_add_f32_e32 v214, v214, v215
	v_add_f32_e32 v216, v216, v217
	v_add_f32_e32 v218, v218, v219
	v_add_f32_e32 v220, v220, v221
	v_add_f32_e32 v222, v222, v223
	v_add_f32_e32 v224, v224, v225
	v_add_f32_e32 v226, v226, v227
	v_mov_b32_e32 v213, v212
	v_mov_b32_e32 v215, v214
	v_mov_b32_e32 v217, v216
	v_mov_b32_e32 v219, v218
	v_mov_b32_e32 v221, v220
	v_mov_b32_e32 v223, v222
	v_mov_b32_e32 v225, v224
	v_mov_b32_e32 v227, v226
	s_nop 1
	v_permlane32_swap_b32_e32 v212, v213
	v_permlane32_swap_b32_e32 v214, v215
	v_permlane32_swap_b32_e32 v216, v217
	v_permlane32_swap_b32_e32 v218, v219
	v_permlane32_swap_b32_e32 v220, v221
	v_permlane32_swap_b32_e32 v222, v223
	v_permlane32_swap_b32_e32 v224, v225
	v_permlane32_swap_b32_e32 v226, v227
	v_add_f32_e32 v212, v212, v213
	v_add_f32_e32 v214, v214, v215
	v_add_f32_e32 v216, v216, v217
	v_add_f32_e32 v218, v218, v219
	v_add_f32_e32 v220, v220, v221
	v_add_f32_e32 v222, v222, v223
	v_add_f32_e32 v224, v224, v225
	v_add_f32_e32 v226, v226, v227
	v_fmamk_f32 v212, v212, 0x3a800000, v154
	v_fmamk_f32 v214, v214, 0x3a800000, v154
	v_fmamk_f32 v216, v216, 0x3a800000, v154
	v_fmamk_f32 v218, v218, 0x3a800000, v154
	v_fmamk_f32 v220, v220, 0x3a800000, v154
	v_fmamk_f32 v222, v222, 0x3a800000, v154
	v_fmamk_f32 v224, v224, 0x3a800000, v154
	v_fmamk_f32 v226, v226, 0x3a800000, v154
	v_rsq_f32_e32 v212, v212
	v_rsq_f32_e32 v214, v214
	v_rsq_f32_e32 v216, v216
	v_rsq_f32_e32 v218, v218
	v_rsq_f32_e32 v220, v220
	v_rsq_f32_e32 v222, v222
	v_rsq_f32_e32 v224, v224
	v_rsq_f32_e32 v226, v226
	s_nop 0
	v_pk_mul_f32 v[126:127], v[126:127], v[212:213] op_sel_hi:[1,0]
	v_pk_mul_f32 v[124:125], v[124:125], v[212:213] op_sel_hi:[1,0]
	v_pk_mul_f32 v[122:123], v[122:123], v[212:213] op_sel_hi:[1,0]
	v_pk_mul_f32 v[120:121], v[120:121], v[212:213] op_sel_hi:[1,0]
	v_pk_mul_f32 v[118:119], v[118:119], v[212:213] op_sel_hi:[1,0]
	v_pk_mul_f32 v[116:117], v[116:117], v[212:213] op_sel_hi:[1,0]
	v_pk_mul_f32 v[114:115], v[114:115], v[212:213] op_sel_hi:[1,0]
	v_pk_mul_f32 v[112:113], v[112:113], v[212:213] op_sel_hi:[1,0]
	v_max_f32_e32 v112, 0, v112
	v_max_f32_e32 v113, 0, v113
	v_max_f32_e32 v114, 0, v114
	v_max_f32_e32 v115, 0, v115
	v_max_f32_e32 v116, 0, v116
	v_max_f32_e32 v117, 0, v117
	v_max_f32_e32 v118, 0, v118
	v_max_f32_e32 v119, 0, v119
	v_max_f32_e32 v120, 0, v120
	v_max_f32_e32 v121, 0, v121
	v_max_f32_e32 v122, 0, v122
	v_max_f32_e32 v123, 0, v123
	v_max_f32_e32 v124, 0, v124
	v_max_f32_e32 v125, 0, v125
	v_max_f32_e32 v126, 0, v126
	v_max_f32_e32 v127, 0, v127
	v_pk_mul_f32 v[112:113], v[112:113], v[112:113]
	v_pk_mul_f32 v[114:115], v[114:115], v[114:115]
	v_pk_mul_f32 v[116:117], v[116:117], v[116:117]
	v_pk_mul_f32 v[118:119], v[118:119], v[118:119]
	v_pk_mul_f32 v[120:121], v[120:121], v[120:121]
	v_pk_mul_f32 v[122:123], v[122:123], v[122:123]
	v_pk_mul_f32 v[124:125], v[124:125], v[124:125]
	v_pk_mul_f32 v[126:127], v[126:127], v[126:127]
	v_cvt_pk_bf16_f32 v156, v124, v125
	v_cvt_pk_bf16_f32 v157, v126, v127
	v_cvt_pk_bf16_f32 v158, v120, v121
	v_cvt_pk_bf16_f32 v159, v122, v123
	v_cvt_pk_bf16_f32 v160, v116, v117
	v_cvt_pk_bf16_f32 v161, v118, v119
	v_cvt_pk_bf16_f32 v162, v112, v113
	v_cvt_pk_bf16_f32 v163, v114, v115
	global_store_dwordx4 v172, v[156:159], s[6:7]
	global_store_dwordx4 v172, v[160:163], s[6:7] offset:256
	v_pk_mul_f32 v[110:111], v[110:111], v[214:215] op_sel_hi:[1,0]
	v_pk_mul_f32 v[108:109], v[108:109], v[214:215] op_sel_hi:[1,0]
	v_pk_mul_f32 v[106:107], v[106:107], v[214:215] op_sel_hi:[1,0]
	v_pk_mul_f32 v[104:105], v[104:105], v[214:215] op_sel_hi:[1,0]
; __device__ __forceinline__ u32x4 pack8f(const f32x4& a, const f32x4& b) { u32x4 w; w.x = ::pk2(a[0], a[1]); w.y = ::pk2(a[2], a[3]); w.z = ::pk2(b[0], b[1]); w.w = ::pk2(b[2], b[3]); return w; }
;     __device__ __forceinline__ void operator()(const f32x4 (&acc)[2][2][4][2], const Unit& u, int wr, int wc, int fr, int fq) const {
;     ...
; #pragma unroll
;                 for (int bj = 0; bj < 2; ++bj) {
;                     const int c = pn * BM + bj * HALF + cl;
;                     f32x4 v0 = acc[ai][bj][m][0] * rstd, v1 = acc[ai][bj][m][1] * rstd;
;                     if (ACT == 1) {
; #pragma unroll
;                         for (int e = 0; e < 4; ++e) { const float a0 = fmaxf(v0[e], 0.f), a1 = fmaxf(v1[e], 0.f); v0[e] = a0 * a0; v1[e] = a1 * a1; }
;                     }
;                     *(u32x4*)(O + (size_t)row * ldc + c) = pack8f(v0, v1);
;                 }
	v_pk_mul_f32 v[102:103], v[102:103], v[214:215] op_sel_hi:[1,0]
	v_pk_mul_f32 v[100:101], v[100:101], v[214:215] op_sel_hi:[1,0]
	v_pk_mul_f32 v[98:99], v[98:99], v[214:215] op_sel_hi:[1,0]
	v_pk_mul_f32 v[96:97], v[96:97], v[214:215] op_sel_hi:[1,0]
	v_max_f32_e32 v96, 0, v96
	v_max_f32_e32 v97, 0, v97
	v_max_f32_e32 v98, 0, v98
	v_max_f32_e32 v99, 0, v99
	v_max_f32_e32 v100, 0, v100
	v_max_f32_e32 v101, 0, v101
	v_max_f32_e32 v102, 0, v102
	v_max_f32_e32 v103, 0, v103
	v_max_f32_e32 v104, 0, v104
	v_max_f32_e32 v105, 0, v105
	v_max_f32_e32 v106, 0, v106
	v_max_f32_e32 v107, 0, v107
	v_max_f32_e32 v108, 0, v108
	v_max_f32_e32 v109, 0, v109
	v_max_f32_e32 v110, 0, v110
	v_max_f32_e32 v111, 0, v111
	v_pk_mul_f32 v[96:97], v[96:97], v[96:97]
	v_pk_mul_f32 v[98:99], v[98:99], v[98:99]
	v_pk_mul_f32 v[100:101], v[100:101], v[100:101]
	v_pk_mul_f32 v[102:103], v[102:103], v[102:103]
	v_pk_mul_f32 v[104:105], v[104:105], v[104:105]
	v_pk_mul_f32 v[106:107], v[106:107], v[106:107]
	v_pk_mul_f32 v[108:109], v[108:109], v[108:109]
	v_pk_mul_f32 v[110:111], v[110:111], v[110:111]
	v_cvt_pk_bf16_f32 v164, v108, v109
	v_cvt_pk_bf16_f32 v165, v110, v111
	v_cvt_pk_bf16_f32 v166, v104, v105
	v_cvt_pk_bf16_f32 v167, v106, v107
	v_cvt_pk_bf16_f32 v168, v100, v101
	v_cvt_pk_bf16_f32 v169, v102, v103
	v_cvt_pk_bf16_f32 v170, v96, v97
	v_cvt_pk_bf16_f32 v171, v98, v99
	v_add_u32_e32 v173, 0x20000, v172
	global_store_dwordx4 v173, v[164:167], s[6:7]
	global_store_dwordx4 v173, v[168:171], s[6:7] offset:256
	v_pk_mul_f32 v[94:95], v[94:95], v[216:217] op_sel_hi:[1,0]
	v_pk_mul_f32 v[92:93], v[92:93], v[216:217] op_sel_hi:[1,0]
	v_pk_mul_f32 v[90:91], v[90:91], v[216:217] op_sel_hi:[1,0]
	v_pk_mul_f32 v[88:89], v[88:89], v[216:217] op_sel_hi:[1,0]
	v_pk_mul_f32 v[86:87], v[86:87], v[216:217] op_sel_hi:[1,0]
	v_pk_mul_f32 v[84:85], v[84:85], v[216:217] op_sel_hi:[1,0]
	v_pk_mul_f32 v[82:83], v[82:83], v[216:217] op_sel_hi:[1,0]
	v_pk_mul_f32 v[80:81], v[80:81], v[216:217] op_sel_hi:[1,0]
	v_max_f32_e32 v80, 0, v80
	v_max_f32_e32 v81, 0, v81
	v_max_f32_e32 v82, 0, v82
	v_max_f32_e32 v83, 0, v83
	v_max_f32_e32 v84, 0, v84
	v_max_f32_e32 v85, 0, v85
	v_max_f32_e32 v86, 0, v86
	v_max_f32_e32 v87, 0, v87
	v_max_f32_e32 v88, 0, v88
	v_max_f32_e32 v89, 0, v89
	v_max_f32_e32 v90, 0, v90
	v_max_f32_e32 v91, 0, v91
	v_max_f32_e32 v92, 0, v92
	v_max_f32_e32 v93, 0, v93
	v_max_f32_e32 v94, 0, v94
	v_max_f32_e32 v95, 0, v95
	v_pk_mul_f32 v[80:81], v[80:81], v[80:81]
	v_pk_mul_f32 v[82:83], v[82:83], v[82:83]
	v_pk_mul_f32 v[84:85], v[84:85], v[84:85]
	v_pk_mul_f32 v[86:87], v[86:87], v[86:87]
	v_pk_mul_f32 v[88:89], v[88:89], v[88:89]
	v_pk_mul_f32 v[90:91], v[90:91], v[90:91]
	v_pk_mul_f32 v[92:93], v[92:93], v[92:93]
	v_pk_mul_f32 v[94:95], v[94:95], v[94:95]
	v_cvt_pk_bf16_f32 v156, v92, v93
	v_cvt_pk_bf16_f32 v157, v94, v95
	v_cvt_pk_bf16_f32 v158, v88, v89
	v_cvt_pk_bf16_f32 v159, v90, v91
	v_cvt_pk_bf16_f32 v160, v84, v85
	v_cvt_pk_bf16_f32 v161, v86, v87
	v_cvt_pk_bf16_f32 v162, v80, v81
	v_cvt_pk_bf16_f32 v163, v82, v83
	v_add_u32_e32 v174, 0x40000, v172
	global_store_dwordx4 v174, v[156:159], s[6:7]
	global_store_dwordx4 v174, v[160:163], s[6:7] offset:256
	v_pk_mul_f32 v[78:79], v[78:79], v[218:219] op_sel_hi:[1,0]
	v_pk_mul_f32 v[76:77], v[76:77], v[218:219] op_sel_hi:[1,0]
	v_pk_mul_f32 v[74:75], v[74:75], v[218:219] op_sel_hi:[1,0]
	v_pk_mul_f32 v[72:73], v[72:73], v[218:219] op_sel_hi:[1,0]
	v_pk_mul_f32 v[70:71], v[70:71], v[218:219] op_sel_hi:[1,0]
	v_pk_mul_f32 v[68:69], v[68:69], v[218:219] op_sel_hi:[1,0]
	v_pk_mul_f32 v[66:67], v[66:67], v[218:219] op_sel_hi:[1,0]
	v_pk_mul_f32 v[64:65], v[64:65], v[218:219] op_sel_hi:[1,0]
	v_max_f32_e32 v64, 0, v64
	v_max_f32_e32 v65, 0, v65
	v_max_f32_e32 v66, 0, v66
	v_max_f32_e32 v67, 0, v67
	v_max_f32_e32 v68, 0, v68
	v_max_f32_e32 v69, 0, v69
	v_max_f32_e32 v70, 0, v70
	v_max_f32_e32 v71, 0, v71
	v_max_f32_e32 v72, 0, v72
	v_max_f32_e32 v73, 0, v73
	v_max_f32_e32 v74, 0, v74
	v_max_f32_e32 v75, 0, v75
	v_max_f32_e32 v76, 0, v76
	v_max_f32_e32 v77, 0, v77
	v_max_f32_e32 v78, 0, v78
	v_max_f32_e32 v79, 0, v79
	v_pk_mul_f32 v[64:65], v[64:65], v[64:65]
	v_pk_mul_f32 v[66:67], v[66:67], v[66:67]
	v_pk_mul_f32 v[68:69], v[68:69], v[68:69]
	v_pk_mul_f32 v[70:71], v[70:71], v[70:71]
	v_pk_mul_f32 v[72:73], v[72:73], v[72:73]
	v_pk_mul_f32 v[74:75], v[74:75], v[74:75]
	v_pk_mul_f32 v[76:77], v[76:77], v[76:77]
	v_pk_mul_f32 v[78:79], v[78:79], v[78:79]
	v_cvt_pk_bf16_f32 v164, v76, v77
	v_cvt_pk_bf16_f32 v165, v78, v79
	v_cvt_pk_bf16_f32 v166, v72, v73
	v_cvt_pk_bf16_f32 v167, v74, v75
	v_cvt_pk_bf16_f32 v168, v68, v69
	v_cvt_pk_bf16_f32 v169, v70, v71
	v_cvt_pk_bf16_f32 v170, v64, v65
	v_cvt_pk_bf16_f32 v171, v66, v67
	v_add_u32_e32 v173, 0x60000, v172
	global_store_dwordx4 v173, v[164:167], s[6:7]
	global_store_dwordx4 v173, v[168:171], s[6:7] offset:256
	v_pk_mul_f32 v[62:63], v[62:63], v[220:221] op_sel_hi:[1,0]
	v_pk_mul_f32 v[60:61], v[60:61], v[220:221] op_sel_hi:[1,0]
	v_pk_mul_f32 v[58:59], v[58:59], v[220:221] op_sel_hi:[1,0]
	v_pk_mul_f32 v[56:57], v[56:57], v[220:221] op_sel_hi:[1,0]
	v_pk_mul_f32 v[54:55], v[54:55], v[220:221] op_sel_hi:[1,0]
	v_pk_mul_f32 v[52:53], v[52:53], v[220:221] op_sel_hi:[1,0]
	v_pk_mul_f32 v[50:51], v[50:51], v[220:221] op_sel_hi:[1,0]
	v_pk_mul_f32 v[48:49], v[48:49], v[220:221] op_sel_hi:[1,0]
	v_max_f32_e32 v48, 0, v48
	v_max_f32_e32 v49, 0, v49
	v_max_f32_e32 v50, 0, v50
	v_max_f32_e32 v51, 0, v51
	v_max_f32_e32 v52, 0, v52
	v_max_f32_e32 v53, 0, v53
	v_max_f32_e32 v54, 0, v54
	v_max_f32_e32 v55, 0, v55
	v_max_f32_e32 v56, 0, v56
	v_max_f32_e32 v57, 0, v57
	v_max_f32_e32 v58, 0, v58
; __device__ __forceinline__ u32x4 pack8f(const f32x4& a, const f32x4& b) { u32x4 w; w.x = ::pk2(a[0], a[1]); w.y = ::pk2(a[2], a[3]); w.z = ::pk2(b[0], b[1]); w.w = ::pk2(b[2], b[3]); return w; }
;     __device__ __forceinline__ void operator()(const f32x4 (&acc)[2][2][4][2], const Unit& u, int wr, int wc, int fr, int fq) const {
;     ...
; #pragma unroll
;                 for (int bj = 0; bj < 2; ++bj) {
;                     const int c = pn * BM + bj * HALF + cl;
;                     f32x4 v0 = acc[ai][bj][m][0] * rstd, v1 = acc[ai][bj][m][1] * rstd;
;                     if (ACT == 1) {
; #pragma unroll
;                         for (int e = 0; e < 4; ++e) { const float a0 = fmaxf(v0[e], 0.f), a1 = fmaxf(v1[e], 0.f); v0[e] = a0 * a0; v1[e] = a1 * a1; }
;                     }
;                     *(u32x4*)(O + (size_t)row * ldc + c) = pack8f(v0, v1);
;                 }
	v_max_f32_e32 v59, 0, v59
	v_max_f32_e32 v60, 0, v60
	v_max_f32_e32 v61, 0, v61
	v_max_f32_e32 v62, 0, v62
	v_max_f32_e32 v63, 0, v63
	v_pk_mul_f32 v[48:49], v[48:49], v[48:49]
	v_pk_mul_f32 v[50:51], v[50:51], v[50:51]
	v_pk_mul_f32 v[52:53], v[52:53], v[52:53]
	v_pk_mul_f32 v[54:55], v[54:55], v[54:55]
	v_pk_mul_f32 v[56:57], v[56:57], v[56:57]
	v_pk_mul_f32 v[58:59], v[58:59], v[58:59]
	v_pk_mul_f32 v[60:61], v[60:61], v[60:61]
	v_pk_mul_f32 v[62:63], v[62:63], v[62:63]
	v_cvt_pk_bf16_f32 v156, v60, v61
	v_cvt_pk_bf16_f32 v157, v62, v63
	v_cvt_pk_bf16_f32 v158, v56, v57
	v_cvt_pk_bf16_f32 v159, v58, v59
	v_cvt_pk_bf16_f32 v160, v52, v53
	v_cvt_pk_bf16_f32 v161, v54, v55
	v_cvt_pk_bf16_f32 v162, v48, v49
	v_cvt_pk_bf16_f32 v163, v50, v51
	v_add_u32_e32 v174, 0x100000, v172
	global_store_dwordx4 v174, v[156:159], s[6:7]
	global_store_dwordx4 v174, v[160:163], s[6:7] offset:256
	v_pk_mul_f32 v[46:47], v[46:47], v[222:223] op_sel_hi:[1,0]
	v_pk_mul_f32 v[44:45], v[44:45], v[222:223] op_sel_hi:[1,0]
	v_pk_mul_f32 v[42:43], v[42:43], v[222:223] op_sel_hi:[1,0]
	v_pk_mul_f32 v[40:41], v[40:41], v[222:223] op_sel_hi:[1,0]
	v_pk_mul_f32 v[38:39], v[38:39], v[222:223] op_sel_hi:[1,0]
	v_pk_mul_f32 v[36:37], v[36:37], v[222:223] op_sel_hi:[1,0]
	v_pk_mul_f32 v[34:35], v[34:35], v[222:223] op_sel_hi:[1,0]
	v_pk_mul_f32 v[32:33], v[32:33], v[222:223] op_sel_hi:[1,0]
	v_max_f32_e32 v32, 0, v32
	v_max_f32_e32 v33, 0, v33
	v_max_f32_e32 v34, 0, v34
	v_max_f32_e32 v35, 0, v35
	v_max_f32_e32 v36, 0, v36
	v_max_f32_e32 v37, 0, v37
	v_max_f32_e32 v38, 0, v38
	v_max_f32_e32 v39, 0, v39
	v_max_f32_e32 v40, 0, v40
	v_max_f32_e32 v41, 0, v41
	v_max_f32_e32 v42, 0, v42
	v_max_f32_e32 v43, 0, v43
	v_max_f32_e32 v44, 0, v44
	v_max_f32_e32 v45, 0, v45
	v_max_f32_e32 v46, 0, v46
	v_max_f32_e32 v47, 0, v47
	v_pk_mul_f32 v[32:33], v[32:33], v[32:33]
	v_pk_mul_f32 v[34:35], v[34:35], v[34:35]
	v_pk_mul_f32 v[36:37], v[36:37], v[36:37]
	v_pk_mul_f32 v[38:39], v[38:39], v[38:39]
	v_pk_mul_f32 v[40:41], v[40:41], v[40:41]
	v_pk_mul_f32 v[42:43], v[42:43], v[42:43]
	v_pk_mul_f32 v[44:45], v[44:45], v[44:45]
	v_pk_mul_f32 v[46:47], v[46:47], v[46:47]
	v_cvt_pk_bf16_f32 v164, v44, v45
	v_cvt_pk_bf16_f32 v165, v46, v47
	v_cvt_pk_bf16_f32 v166, v40, v41
	v_cvt_pk_bf16_f32 v167, v42, v43
	v_cvt_pk_bf16_f32 v168, v36, v37
	v_cvt_pk_bf16_f32 v169, v38, v39
	v_cvt_pk_bf16_f32 v170, v32, v33
	v_cvt_pk_bf16_f32 v171, v34, v35
	v_add_u32_e32 v173, 0x120000, v172
	global_store_dwordx4 v173, v[164:167], s[6:7]
	global_store_dwordx4 v173, v[168:171], s[6:7] offset:256
	v_pk_mul_f32 v[30:31], v[30:31], v[224:225] op_sel_hi:[1,0]
	v_pk_mul_f32 v[28:29], v[28:29], v[224:225] op_sel_hi:[1,0]
	v_pk_mul_f32 v[26:27], v[26:27], v[224:225] op_sel_hi:[1,0]
	v_pk_mul_f32 v[24:25], v[24:25], v[224:225] op_sel_hi:[1,0]
	v_pk_mul_f32 v[22:23], v[22:23], v[224:225] op_sel_hi:[1,0]
	v_pk_mul_f32 v[20:21], v[20:21], v[224:225] op_sel_hi:[1,0]
	v_pk_mul_f32 v[18:19], v[18:19], v[224:225] op_sel_hi:[1,0]
	v_pk_mul_f32 v[16:17], v[16:17], v[224:225] op_sel_hi:[1,0]
	v_max_f32_e32 v16, 0, v16
	v_max_f32_e32 v17, 0, v17
	v_max_f32_e32 v18, 0, v18
	v_max_f32_e32 v19, 0, v19
	v_max_f32_e32 v20, 0, v20
	v_max_f32_e32 v21, 0, v21
	v_max_f32_e32 v22, 0, v22
	v_max_f32_e32 v23, 0, v23
	v_max_f32_e32 v24, 0, v24
	v_max_f32_e32 v25, 0, v25
	v_max_f32_e32 v26, 0, v26
	v_max_f32_e32 v27, 0, v27
	v_max_f32_e32 v28, 0, v28
	v_max_f32_e32 v29, 0, v29
	v_max_f32_e32 v30, 0, v30
	v_max_f32_e32 v31, 0, v31
	v_pk_mul_f32 v[16:17], v[16:17], v[16:17]
	v_pk_mul_f32 v[18:19], v[18:19], v[18:19]
	v_pk_mul_f32 v[20:21], v[20:21], v[20:21]
	v_pk_mul_f32 v[22:23], v[22:23], v[22:23]
	v_pk_mul_f32 v[24:25], v[24:25], v[24:25]
	v_pk_mul_f32 v[26:27], v[26:27], v[26:27]
	v_pk_mul_f32 v[28:29], v[28:29], v[28:29]
	v_pk_mul_f32 v[30:31], v[30:31], v[30:31]
	v_cvt_pk_bf16_f32 v156, v28, v29
	v_cvt_pk_bf16_f32 v157, v30, v31
	v_cvt_pk_bf16_f32 v158, v24, v25
	v_cvt_pk_bf16_f32 v159, v26, v27
	v_cvt_pk_bf16_f32 v160, v20, v21
	v_cvt_pk_bf16_f32 v161, v22, v23
	v_cvt_pk_bf16_f32 v162, v16, v17
	v_cvt_pk_bf16_f32 v163, v18, v19
	v_add_u32_e32 v174, 0x140000, v172
	global_store_dwordx4 v174, v[156:159], s[6:7]
	global_store_dwordx4 v174, v[160:163], s[6:7] offset:256
	v_pk_mul_f32 v[14:15], v[14:15], v[226:227] op_sel_hi:[1,0]
	v_pk_mul_f32 v[12:13], v[12:13], v[226:227] op_sel_hi:[1,0]
	v_pk_mul_f32 v[10:11], v[10:11], v[226:227] op_sel_hi:[1,0]
	v_pk_mul_f32 v[8:9], v[8:9], v[226:227] op_sel_hi:[1,0]
	v_pk_mul_f32 v[6:7], v[6:7], v[226:227] op_sel_hi:[1,0]
	v_pk_mul_f32 v[4:5], v[4:5], v[226:227] op_sel_hi:[1,0]
	v_pk_mul_f32 v[2:3], v[2:3], v[226:227] op_sel_hi:[1,0]
	v_pk_mul_f32 v[0:1], v[0:1], v[226:227] op_sel_hi:[1,0]
	v_max_f32_e32 v0, 0, v0
	v_max_f32_e32 v1, 0, v1
	v_max_f32_e32 v2, 0, v2
	v_max_f32_e32 v3, 0, v3
	v_max_f32_e32 v4, 0, v4
	v_max_f32_e32 v5, 0, v5
	v_max_f32_e32 v6, 0, v6
	v_max_f32_e32 v7, 0, v7
	v_max_f32_e32 v8, 0, v8
	v_max_f32_e32 v9, 0, v9
	v_max_f32_e32 v10, 0, v10
	v_max_f32_e32 v11, 0, v11
	v_max_f32_e32 v12, 0, v12
	v_max_f32_e32 v13, 0, v13
	v_max_f32_e32 v14, 0, v14
	v_max_f32_e32 v15, 0, v15
	v_pk_mul_f32 v[0:1], v[0:1], v[0:1]
	v_pk_mul_f32 v[2:3], v[2:3], v[2:3]
	v_pk_mul_f32 v[4:5], v[4:5], v[4:5]
	v_pk_mul_f32 v[6:7], v[6:7], v[6:7]
	v_pk_mul_f32 v[8:9], v[8:9], v[8:9]
	v_pk_mul_f32 v[10:11], v[10:11], v[10:11]
	v_pk_mul_f32 v[12:13], v[12:13], v[12:13]
	v_pk_mul_f32 v[14:15], v[14:15], v[14:15]
	v_cvt_pk_bf16_f32 v164, v12, v13
	v_cvt_pk_bf16_f32 v165, v14, v15
	v_cvt_pk_bf16_f32 v166, v8, v9
	v_cvt_pk_bf16_f32 v167, v10, v11
	v_cvt_pk_bf16_f32 v168, v4, v5
	v_cvt_pk_bf16_f32 v169, v6, v7
	v_cvt_pk_bf16_f32 v170, v0, v1
	v_cvt_pk_bf16_f32 v171, v2, v3
	v_add_u32_e32 v173, 0x160000, v172
	global_store_dwordx4 v173, v[164:167], s[6:7]
	global_store_dwordx4 v173, v[168:171], s[6:7] offset:256
	s_andn2_b64 vcc, exec, s[0:1]
	s_mov_b64 s[0:1], -1
	s_cbranch_vccnz .LBB0_1709
	s_andn2_b64 vcc, exec, s[4:5]
	s_cbranch_vccnz .LBB0_1708
	s_barrier
	s_branch .LBB0_1708

;     __device__ __forceinline__ void operator()(const f32x4 (&acc)[2][2][4][2], const Unit& u, int wr, int wc, int fr, int fq) const {
;     ...
;                 const int row = u.pm * BM + ai * HALF + wr * 64 + m * 16 + fr;
;                 const float* rp = row < MP ? resid_p + (size_t)row * DM : resid_s + (size_t)(row - MP) * DM;
;                 float ss = 0.f;
; #pragma unroll
;                 for (int bj = 0; bj < 2; ++bj) {
;                     const int c = pn * BM + bj * HALF + cl;
;                     const f32x4 v0 = acc[ai][bj][m][0] + *(const f32x4*)(rp + c), v1 = acc[ai][bj][m][1] + *(const f32x4*)(rp + c + 4);
;                     *(f32x4*)(y + (size_t)row * DM + c) = v0; *(f32x4*)(y + (size_t)row * DM + c + 4) = v1;
.LBB0_1759:
	s_lshl_b32 s13, s22, 8
	v_add_u32_e32 v148, s13, v154
	v_cmp_lt_i32_e32 vcc, s47, v148
	s_and_saveexec_b64 s[22:23], vcc
	s_xor_b64 s[22:23], exec, s[22:23]
	v_add_u32_e32 v136, 0xffff0000, v148
	v_lshlrev_b64 v[146:147], 12, v[136:137]
	v_mov_b32_e32 v149, v137
	v_lshl_add_u64 v[152:153], s[6:7], 0, v[146:147]
	v_lshlrev_b64 v[150:151], 12, v[148:149]
	s_andn2_saveexec_b64 s[22:23], s[22:23]
	v_ashrrev_i32_e32 v149, 31, v148
	v_lshlrev_b64 v[150:151], 12, v[148:149]
	v_lshl_add_u64 v[152:153], s[82:83], 0, v[150:151]
	s_or_b64 exec, exec, s[22:23]
	v_lshl_or_b32 v146, s20, 8, v156
	v_ashrrev_i32_e32 v147, 31, v146
	v_lshlrev_b64 v[146:147], 2, v[146:147]
	v_lshl_add_u64 v[152:153], v[152:153], 0, v[146:147]
	global_load_dwordx4 v[164:167], v[152:153], off
	global_load_dwordx4 v[168:171], v[152:153], off offset:16
	v_lshl_add_u64 v[150:151], s[82:83], 0, v[150:151]
	v_lshl_add_u64 v[172:173], v[150:151], 0, v[146:147]
	s_waitcnt vmcnt(0)
	v_pk_add_f32 v[126:127], v[126:127], v[166:167]
	v_pk_add_f32 v[124:125], v[124:125], v[164:165]
	v_pk_add_f32 v[122:123], v[122:123], v[170:171]
	v_pk_add_f32 v[120:121], v[120:121], v[168:169]
	global_store_dwordx4 v[172:173], v[124:127], off
	global_store_dwordx4 v[172:173], v[120:123], off offset:16
	global_load_dwordx4 v[122:125], v[152:153], off offset:512
	s_nop 0
	global_load_dwordx4 v[150:153], v[152:153], off offset:528
	v_add_u32_e32 v120, s13, v157
	v_cmp_lt_i32_e32 vcc, s47, v120
	s_waitcnt vmcnt(1)
	v_pk_add_f32 v[118:119], v[118:119], v[124:125]
	v_pk_add_f32 v[116:117], v[116:117], v[122:123]
	s_waitcnt vmcnt(0)
	v_pk_add_f32 v[114:115], v[114:115], v[152:153]
	v_pk_add_f32 v[112:113], v[112:113], v[150:151]
	global_store_dwordx4 v[172:173], v[116:119], off offset:512
	global_store_dwordx4 v[172:173], v[112:115], off offset:528
	s_and_saveexec_b64 s[20:21], vcc
	s_xor_b64 s[20:21], exec, s[20:21]
	v_add_u32_e32 v136, 0xffff0000, v120
	v_lshlrev_b64 v[112:113], 12, v[136:137]
	v_mov_b32_e32 v121, v137
	v_lshl_add_u64 v[114:115], s[6:7], 0, v[112:113]
	v_lshlrev_b64 v[112:113], 12, v[120:121]
	s_andn2_saveexec_b64 s[20:21], s[20:21]
	v_ashrrev_i32_e32 v121, 31, v120
	v_lshlrev_b64 v[112:113], 12, v[120:121]
	v_lshl_add_u64 v[114:115], s[82:83], 0, v[112:113]
	s_or_b64 exec, exec, s[20:21]
	v_lshl_add_u64 v[122:123], v[114:115], 0, v[146:147]
	global_load_dwordx4 v[114:117], v[122:123], off
	global_load_dwordx4 v[118:121], v[122:123], off offset:16
	v_lshl_add_u64 v[112:113], s[82:83], 0, v[112:113]
	v_lshl_add_u64 v[124:125], v[112:113], 0, v[146:147]
	s_waitcnt vmcnt(1)
	v_pk_add_f32 v[110:111], v[110:111], v[116:117]
	v_pk_add_f32 v[108:109], v[108:109], v[114:115]
	s_waitcnt vmcnt(0)
	v_pk_add_f32 v[106:107], v[106:107], v[120:121]
	v_pk_add_f32 v[104:105], v[104:105], v[118:119]
	global_store_dwordx4 v[124:125], v[108:111], off
	global_store_dwordx4 v[124:125], v[104:107], off offset:16
	global_load_dwordx4 v[106:109], v[122:123], off offset:512
	s_nop 0
	global_load_dwordx4 v[110:113], v[122:123], off offset:528
	v_add_u32_e32 v104, s13, v158
	v_cmp_lt_i32_e32 vcc, s47, v104
	s_waitcnt vmcnt(1)
	v_pk_add_f32 v[102:103], v[102:103], v[108:109]
	v_pk_add_f32 v[100:101], v[100:101], v[106:107]
	s_waitcnt vmcnt(0)
	v_pk_add_f32 v[98:99], v[98:99], v[112:113]
	v_pk_add_f32 v[96:97], v[96:97], v[110:111]
	global_store_dwordx4 v[124:125], v[100:103], off offset:512
	global_store_dwordx4 v[124:125], v[96:99], off offset:528
	s_and_saveexec_b64 s[20:21], vcc
	s_xor_b64 s[20:21], exec, s[20:21]
	v_add_u32_e32 v136, 0xffff0000, v104
	v_lshlrev_b64 v[96:97], 12, v[136:137]
	v_mov_b32_e32 v105, v137
	v_lshl_add_u64 v[98:99], s[6:7], 0, v[96:97]
	v_lshlrev_b64 v[96:97], 12, v[104:105]
	s_andn2_saveexec_b64 s[20:21], s[20:21]
	v_ashrrev_i32_e32 v105, 31, v104
	v_lshlrev_b64 v[96:97], 12, v[104:105]
	v_lshl_add_u64 v[98:99], s[82:83], 0, v[96:97]
	s_or_b64 exec, exec, s[20:21]
	v_lshl_add_u64 v[106:107], v[98:99], 0, v[146:147]
	global_load_dwordx4 v[98:101], v[106:107], off
	global_load_dwordx4 v[102:105], v[106:107], off offset:16
	v_lshl_add_u64 v[96:97], s[82:83], 0, v[96:97]
	v_lshl_add_u64 v[108:109], v[96:97], 0, v[146:147]
	s_waitcnt vmcnt(1)
	v_pk_add_f32 v[94:95], v[94:95], v[100:101]
	v_pk_add_f32 v[92:93], v[92:93], v[98:99]
	s_waitcnt vmcnt(0)
	v_pk_add_f32 v[90:91], v[90:91], v[104:105]
	v_pk_add_f32 v[88:89], v[88:89], v[102:103]
	global_store_dwordx4 v[108:109], v[92:95], off
	global_store_dwordx4 v[108:109], v[88:91], off offset:16
	global_load_dwordx4 v[90:93], v[106:107], off offset:512
	s_nop 0
	global_load_dwordx4 v[94:97], v[106:107], off offset:528
	v_add_u32_e32 v88, s13, v159
	v_cmp_lt_i32_e32 vcc, s47, v88
	s_waitcnt vmcnt(1)
	v_pk_add_f32 v[86:87], v[86:87], v[92:93]
	v_pk_add_f32 v[84:85], v[84:85], v[90:91]
	s_waitcnt vmcnt(0)
	v_pk_add_f32 v[82:83], v[82:83], v[96:97]
	v_pk_add_f32 v[80:81], v[80:81], v[94:95]
	global_store_dwordx4 v[108:109], v[84:87], off offset:512
	global_store_dwordx4 v[108:109], v[80:83], off offset:528
	s_and_saveexec_b64 s[20:21], vcc
	s_xor_b64 s[20:21], exec, s[20:21]
	v_add_u32_e32 v136, 0xffff0000, v88
	v_lshlrev_b64 v[80:81], 12, v[136:137]
	v_mov_b32_e32 v89, v137
	v_lshl_add_u64 v[82:83], s[6:7], 0, v[80:81]
	v_lshlrev_b64 v[80:81], 12, v[88:89]
	s_andn2_saveexec_b64 s[20:21], s[20:21]
	v_ashrrev_i32_e32 v89, 31, v88
	v_lshlrev_b64 v[80:81], 12, v[88:89]
	v_lshl_add_u64 v[82:83], s[82:83], 0, v[80:81]
	s_or_b64 exec, exec, s[20:21]
	v_lshl_add_u64 v[90:91], v[82:83], 0, v[146:147]
	global_load_dwordx4 v[82:85], v[90:91], off
	global_load_dwordx4 v[86:89], v[90:91], off offset:16
	v_lshl_add_u64 v[80:81], s[82:83], 0, v[80:81]
	v_lshl_add_u64 v[92:93], v[80:81], 0, v[146:147]
	s_waitcnt vmcnt(1)
;     __device__ __forceinline__ void operator()(const f32x4 (&acc)[2][2][4][2], const Unit& u, int wr, int wc, int fr, int fq) const {
;     ...
;                 const int row = u.pm * BM + ai * HALF + wr * 64 + m * 16 + fr;
;                 const float* rp = row < MP ? resid_p + (size_t)row * DM : resid_s + (size_t)(row - MP) * DM;
;                 float ss = 0.f;
; #pragma unroll
;                 for (int bj = 0; bj < 2; ++bj) {
;                     const int c = pn * BM + bj * HALF + cl;
;                     const f32x4 v0 = acc[ai][bj][m][0] + *(const f32x4*)(rp + c), v1 = acc[ai][bj][m][1] + *(const f32x4*)(rp + c + 4);
;                     *(f32x4*)(y + (size_t)row * DM + c) = v0; *(f32x4*)(y + (size_t)row * DM + c + 4) = v1;
	v_pk_add_f32 v[78:79], v[78:79], v[84:85]
	v_pk_add_f32 v[76:77], v[76:77], v[82:83]
	s_waitcnt vmcnt(0)
	v_pk_add_f32 v[74:75], v[74:75], v[88:89]
	v_pk_add_f32 v[72:73], v[72:73], v[86:87]
	global_store_dwordx4 v[92:93], v[76:79], off
	global_store_dwordx4 v[92:93], v[72:75], off offset:16
	global_load_dwordx4 v[74:77], v[90:91], off offset:512
	s_nop 0
	global_load_dwordx4 v[78:81], v[90:91], off offset:528
	v_add_u32_e32 v72, 0x80, v148
	v_cmp_lt_i32_e32 vcc, s47, v72
	s_waitcnt vmcnt(1)
	v_pk_add_f32 v[70:71], v[70:71], v[76:77]
	v_pk_add_f32 v[68:69], v[68:69], v[74:75]
	s_waitcnt vmcnt(0)
	v_pk_add_f32 v[66:67], v[66:67], v[80:81]
	v_pk_add_f32 v[64:65], v[64:65], v[78:79]
	global_store_dwordx4 v[92:93], v[68:71], off offset:512
	global_store_dwordx4 v[92:93], v[64:67], off offset:528
	s_and_saveexec_b64 s[20:21], vcc
	s_xor_b64 s[20:21], exec, s[20:21]
	v_add_u32_e32 v136, 0xffff0000, v72
	v_lshlrev_b64 v[64:65], 12, v[136:137]
	v_mov_b32_e32 v73, v137
	v_lshl_add_u64 v[66:67], s[6:7], 0, v[64:65]
	v_lshlrev_b64 v[64:65], 12, v[72:73]
	s_andn2_saveexec_b64 s[20:21], s[20:21]
	v_ashrrev_i32_e32 v73, 31, v72
	v_lshlrev_b64 v[64:65], 12, v[72:73]
	v_lshl_add_u64 v[66:67], s[82:83], 0, v[64:65]
	s_or_b64 exec, exec, s[20:21]
	v_lshl_add_u64 v[74:75], v[66:67], 0, v[146:147]
	global_load_dwordx4 v[66:69], v[74:75], off
	global_load_dwordx4 v[70:73], v[74:75], off offset:16
	v_lshl_add_u64 v[64:65], s[82:83], 0, v[64:65]
	v_lshl_add_u64 v[76:77], v[64:65], 0, v[146:147]
	s_waitcnt vmcnt(1)
	v_pk_add_f32 v[62:63], v[62:63], v[68:69]
	v_pk_add_f32 v[60:61], v[60:61], v[66:67]
	s_waitcnt vmcnt(0)
	v_pk_add_f32 v[58:59], v[58:59], v[72:73]
	v_pk_add_f32 v[56:57], v[56:57], v[70:71]
	global_store_dwordx4 v[76:77], v[60:63], off
	global_store_dwordx4 v[76:77], v[56:59], off offset:16
	global_load_dwordx4 v[58:61], v[74:75], off offset:512
	s_nop 0
	global_load_dwordx4 v[62:65], v[74:75], off offset:528
	v_add_u32_e32 v56, 0x90, v148
	v_cmp_lt_i32_e32 vcc, s47, v56
	s_waitcnt vmcnt(1)
	v_pk_add_f32 v[54:55], v[54:55], v[60:61]
	v_pk_add_f32 v[52:53], v[52:53], v[58:59]
	s_waitcnt vmcnt(0)
	v_pk_add_f32 v[50:51], v[50:51], v[64:65]
	v_pk_add_f32 v[48:49], v[48:49], v[62:63]
	global_store_dwordx4 v[76:77], v[52:55], off offset:512
	global_store_dwordx4 v[76:77], v[48:51], off offset:528
	s_and_saveexec_b64 s[20:21], vcc
	s_xor_b64 s[20:21], exec, s[20:21]
	v_add_u32_e32 v136, 0xffff0000, v56
	v_lshlrev_b64 v[48:49], 12, v[136:137]
	v_mov_b32_e32 v57, v137
	v_lshl_add_u64 v[50:51], s[6:7], 0, v[48:49]
	v_lshlrev_b64 v[48:49], 12, v[56:57]
	s_andn2_saveexec_b64 s[20:21], s[20:21]
	v_ashrrev_i32_e32 v57, 31, v56
	v_lshlrev_b64 v[48:49], 12, v[56:57]
	v_lshl_add_u64 v[50:51], s[82:83], 0, v[48:49]
	s_or_b64 exec, exec, s[20:21]
	v_lshl_add_u64 v[58:59], v[50:51], 0, v[146:147]
	global_load_dwordx4 v[50:53], v[58:59], off
	global_load_dwordx4 v[54:57], v[58:59], off offset:16
	v_lshl_add_u64 v[48:49], s[82:83], 0, v[48:49]
	v_lshl_add_u64 v[60:61], v[48:49], 0, v[146:147]
	s_waitcnt vmcnt(1)
	v_pk_add_f32 v[46:47], v[46:47], v[52:53]
	v_pk_add_f32 v[44:45], v[44:45], v[50:51]
	s_waitcnt vmcnt(0)
	v_pk_add_f32 v[42:43], v[42:43], v[56:57]
	v_pk_add_f32 v[40:41], v[40:41], v[54:55]
	global_store_dwordx4 v[60:61], v[44:47], off
	global_store_dwordx4 v[60:61], v[40:43], off offset:16
	global_load_dwordx4 v[42:45], v[58:59], off offset:512
	s_nop 0
	global_load_dwordx4 v[46:49], v[58:59], off offset:528
	v_add_u32_e32 v40, 0xa0, v148
	v_cmp_lt_i32_e32 vcc, s47, v40
	s_waitcnt vmcnt(1)
	v_pk_add_f32 v[38:39], v[38:39], v[44:45]
	v_pk_add_f32 v[36:37], v[36:37], v[42:43]
	s_waitcnt vmcnt(0)
	v_pk_add_f32 v[34:35], v[34:35], v[48:49]
	v_pk_add_f32 v[32:33], v[32:33], v[46:47]
	global_store_dwordx4 v[60:61], v[36:39], off offset:512
	global_store_dwordx4 v[60:61], v[32:35], off offset:528
	s_and_saveexec_b64 s[20:21], vcc
	s_xor_b64 s[20:21], exec, s[20:21]
	v_add_u32_e32 v136, 0xffff0000, v40
	v_lshlrev_b64 v[32:33], 12, v[136:137]
	v_mov_b32_e32 v41, v137
	v_lshl_add_u64 v[34:35], s[6:7], 0, v[32:33]
	v_lshlrev_b64 v[32:33], 12, v[40:41]
	s_andn2_saveexec_b64 s[20:21], s[20:21]
	v_ashrrev_i32_e32 v41, 31, v40
	v_lshlrev_b64 v[32:33], 12, v[40:41]
	v_lshl_add_u64 v[34:35], s[82:83], 0, v[32:33]
	s_or_b64 exec, exec, s[20:21]
	v_lshl_add_u64 v[42:43], v[34:35], 0, v[146:147]
	global_load_dwordx4 v[34:37], v[42:43], off
	global_load_dwordx4 v[38:41], v[42:43], off offset:16
	v_lshl_add_u64 v[32:33], s[82:83], 0, v[32:33]
	v_lshl_add_u64 v[44:45], v[32:33], 0, v[146:147]
	s_waitcnt vmcnt(1)
	v_pk_add_f32 v[30:31], v[30:31], v[36:37]
	v_pk_add_f32 v[28:29], v[28:29], v[34:35]
	s_waitcnt vmcnt(0)
	v_pk_add_f32 v[26:27], v[26:27], v[40:41]
	v_pk_add_f32 v[24:25], v[24:25], v[38:39]
	global_store_dwordx4 v[44:45], v[28:31], off
	global_store_dwordx4 v[44:45], v[24:27], off offset:16
	global_load_dwordx4 v[26:29], v[42:43], off offset:512
	s_nop 0
	global_load_dwordx4 v[30:33], v[42:43], off offset:528
	v_add_u32_e32 v24, 0xb0, v148
	v_cmp_lt_i32_e32 vcc, s47, v24
	s_waitcnt vmcnt(1)
	v_pk_add_f32 v[22:23], v[22:23], v[28:29]
	v_pk_add_f32 v[20:21], v[20:21], v[26:27]
	s_waitcnt vmcnt(0)
	v_pk_add_f32 v[18:19], v[18:19], v[32:33]
	v_pk_add_f32 v[16:17], v[16:17], v[30:31]
	global_store_dwordx4 v[44:45], v[20:23], off offset:512
	global_store_dwordx4 v[44:45], v[16:19], off offset:528
	s_and_saveexec_b64 s[20:21], vcc
	s_xor_b64 s[20:21], exec, s[20:21]
	v_add_u32_e32 v136, 0xffff0000, v24
	v_lshlrev_b64 v[16:17], 12, v[136:137]
	v_mov_b32_e32 v25, v137
	v_lshl_add_u64 v[18:19], s[6:7], 0, v[16:17]
	v_lshlrev_b64 v[16:17], 12, v[24:25]
	s_andn2_saveexec_b64 s[20:21], s[20:21]
	v_ashrrev_i32_e32 v25, 31, v24
	v_lshlrev_b64 v[16:17], 12, v[24:25]
	v_lshl_add_u64 v[18:19], s[82:83], 0, v[16:17]
	s_or_b64 exec, exec, s[20:21]
	v_lshl_add_u64 v[26:27], v[18:19], 0, v[146:147]
	global_load_dwordx4 v[18:21], v[26:27], off
	global_load_dwordx4 v[22:25], v[26:27], off offset:16
	v_lshl_add_u64 v[16:17], s[82:83], 0, v[16:17]
	v_lshl_add_u64 v[16:17], v[16:17], 0, v[146:147]
	s_andn2_b64 vcc, exec, s[0:1]
	s_mov_b64 s[0:1], -1
	s_waitcnt vmcnt(1)
	v_pk_add_f32 v[14:15], v[14:15], v[20:21]
	v_pk_add_f32 v[12:13], v[12:13], v[18:19]
	s_waitcnt vmcnt(0)
	v_pk_add_f32 v[10:11], v[10:11], v[24:25]
	v_pk_add_f32 v[8:9], v[8:9], v[22:23]
	global_store_dwordx4 v[16:17], v[12:15], off
	global_store_dwordx4 v[16:17], v[8:11], off offset:16
	global_load_dwordx4 v[8:11], v[26:27], off offset:512
	s_nop 0
	global_load_dwordx4 v[12:15], v[26:27], off offset:528
	s_waitcnt vmcnt(1)
	v_pk_add_f32 v[6:7], v[6:7], v[10:11]
	v_pk_add_f32 v[4:5], v[4:5], v[8:9]
	s_waitcnt vmcnt(0)
	v_pk_add_f32 v[2:3], v[2:3], v[14:15]
	v_pk_add_f32 v[0:1], v[0:1], v[12:13]
	global_store_dwordx4 v[16:17], v[4:7], off offset:512
	global_store_dwordx4 v[16:17], v[0:3], off offset:528
	s_cbranch_vccnz .LBB0_1748
	s_andn2_b64 vcc, exec, s[4:5]
	s_cbranch_vccnz .LBB0_1747
	s_barrier
	s_branch .LBB0_1747
